# same as previous best but the out-projection tile blocks loop over tiles (tile += gridDim) instead of assuming 256 workgroups
# speedup vs baseline: 1.0015x; 1.0009x over previous
;   constexpr int BM = 256, BN = 128, BK = 64, LR = 144;
;   constexpr int BUFB = (BM + BN) * LR;
;   float* rstdS = (float*)(smem + 2 * BUFB);
;   const int tid = (int)p.tidx, lane = tid & 63, w = (int)p.wv;
;   const int wm = w >> 1, wn = w & 1, l15 = lane & 15, g = lane >> 4;
;   const int KT = K / BK;
;   const int ntiles = mtiles * NT;
;   const float* parts = (const float*)(p.ws + OFF_PARTS);
;   const int srow = tid >> 3, skc = tid & 7;
;   for (int tile0 = rev ? (int)(gridDim.x - 1 - blockIdx.x) : (int)blockIdx.x; tile0 < ntiles * rep; tile0 += gridDim.x) {
;     const int tile = tile0 % ntiles;
;     int mt = tile / NT, nt = tile - mt * NT + nt0;
; template <int EPI>
; __device__ void gemm8_phase(const Params& p, const u16* __restrict__ A, const u16* __restrict__ Bt, const int K, const int nN,
;                             unsigned char* smem, const int rep) {
;     ...
;   const int nM = T_TOK / BM8, nwg = nM * nN;
;   const int wid = (int)p.wv, lane = (int)p.tidx & 63, wr = wid >> 2, wc = wid & 3, fr = lane & 15, fq = lane >> 4;
;   const int nt = K / BK8;
;   const __amdgpu_buffer_rsrc_t rsrc_A = __builtin_amdgcn_make_buffer_rsrc((void*)A, (short)0, T_TOK * K * 2, 0x00020000);
;   const __amdgpu_buffer_rsrc_t rsrc_Bt = __builtin_amdgcn_make_buffer_rsrc((void*)Bt, (short)0, nN * 256 * K * 2, 0x00020000);
;   int voff0, voff1;
;   {
;     int r_, c_;
;     stage_rc((int)p.tidx * 16, r_, c_);
;     voff0 = (r_ * K + c_) * 2;
;     stage_rc((int)p.tidx * 16 + 8192, r_, c_);
;     voff1 = (r_ * K + c_) * 2;
;   }
.LBB0_700:
	s_cmp_lt_i32 s86, 4
	s_cselect_b64 s[0:1], -1, 0
	s_cmp_gt_i32 s88, 2
	s_cselect_b64 s[2:3], -1, 0
	s_and_b64 s[0:1], s[0:1], s[2:3]
	s_andn2_b64 vcc, exec, s[0:1]
	s_cbranch_vccnz .LBB0_891
	s_mov_b32 s8, s84
	s_mov_b32 s22, s85
	v_mbcnt_lo_u32_b32 v0, -1, 0
	v_readlane_b32 s2, v255, 6
	v_mbcnt_hi_u32_b32 v195, -1, v0
	s_nop 0
	v_lshl_add_u32 v252, s2, 6, v195
	v_bfe_i32 v1, v252, 27, 1
	v_lshlrev_b32_e32 v138, 4, v252
	v_lshrrev_b32_e32 v1, 22, v1
	v_add_u32_e32 v1, v138, v1
	v_and_b32_e32 v1, 0xfffffc00, v1
	v_sub_u32_e32 v1, v138, v1
	v_lshrrev_b32_e32 v2, 4, v1
	v_bitop3_b32 v1, v2, v1, 32 bitop3:0x6c
	v_ashrrev_i32_e32 v0, 31, v252
	v_ashrrev_i32_e32 v3, 31, v1
	v_lshrrev_b32_e32 v0, 26, v0
	v_lshrrev_b32_e32 v3, 26, v3
	v_add_u32_e32 v0, v252, v0
	v_add_u32_e32 v3, v1, v3
	v_ashrrev_i32_e32 v0, 6, v0
	v_lshrrev_b32_e32 v4, 6, v3
	v_and_b32_e32 v3, 0xc0, v3
	v_lshlrev_b32_e32 v2, 3, v0
	v_lshlrev_b32_e32 v0, 5, v0
	v_sub_u32_e32 v1, v1, v3
	v_mov_b32_e32 v3, 1
	v_and_b32_e32 v2, 0x1ffff0, v2
	v_and_b32_e32 v0, 32, v0
	v_ashrrev_i16_sdwa v1, v3, sext(v1) dst_sel:DWORD dst_unused:UNUSED_PAD src0_sel:DWORD src1_sel:BYTE_0
	v_add_u32_sdwa v0, v0, sext(v1) dst_sel:DWORD dst_unused:UNUSED_PAD src0_sel:DWORD src1_sel:WORD_0
	v_add_lshl_u32 v1, v4, v2, 12
	v_add_u32_e32 v140, 0x2000, v138
	v_lshl_add_u32 v139, v0, 1, v1
	v_ashrrev_i32_e32 v0, 31, v140
	v_lshrrev_b32_e32 v0, 22, v0
	v_add_u32_e32 v0, v140, v0
	v_ashrrev_i32_e32 v0, 10, v0
	v_mul_i32_i24_e32 v1, 0x400, v0
	v_sub_u32_e32 v1, v140, v1
	v_lshrrev_b32_e32 v2, 4, v1
	v_bitop3_b32 v1, v2, v1, 32 bitop3:0x6c
	v_ashrrev_i32_e32 v4, 31, v1
	v_lshrrev_b32_e32 v4, 26, v4
	v_add_u32_e32 v4, v1, v4
	v_lshrrev_b32_e32 v5, 6, v4
	v_and_b32_e32 v4, 0xc0, v4
	v_lshlrev_b32_e32 v2, 3, v0
	v_lshlrev_b32_e32 v0, 5, v0
	v_sub_u32_e32 v1, v1, v4
	s_add_u32 s12, s8, 0x2242000
	v_and_b32_e32 v2, 0x1ffff0, v2
	v_and_b32_e32 v0, 32, v0
	v_ashrrev_i16_sdwa v1, v3, sext(v1) dst_sel:DWORD dst_unused:UNUSED_PAD src0_sel:DWORD src1_sel:BYTE_0
	s_addc_u32 s0, s22, 0
	v_add_u32_sdwa v0, v0, sext(v1) dst_sel:DWORD dst_unused:UNUSED_PAD src0_sel:DWORD src1_sel:WORD_0
	v_add_lshl_u32 v1, v5, v2, 12
	s_and_b32 s13, s0, 0xffff
	s_and_b32 s9, s22, 0xffff
	v_lshl_add_u32 v141, v0, 1, v1
	v_and_b32_e32 v0, 15, v195
	v_bfe_u32 v1, v252, 4, 2
	s_and_b32 s3, s2, 3
	s_ashr_i32 s4, s2, 2
	s_cmp_eq_u32 s4, 1
	v_lshlrev_b32_e32 v2, 4, v1
	v_lshlrev_b32_e32 v3, 6, v0
	v_lshlrev_b32_e32 v5, 2, v195
	s_cselect_b64 s[0:1], -1, 0
	s_lshl_b32 s5, s3, 12
	v_or_b32_e32 v4, v2, v3
	v_and_b32_e32 v5, 32, v5
	s_mov_b32 s6, 0x10000
	v_bitop3_b32 v6, v4, s6, v5 bitop3:0xde
	s_mov_b32 s6, 0x14000
	s_cmp_lt_u32 s2, 4
	v_bitop3_b32 v7, v4, s6, v5 bitop3:0xde
	s_mov_b32 s6, 0x18000
	s_cselect_b64 s[16:17], -1, 0
	s_lshl_b32 s24, s3, 5
	v_bitop3_b32 v8, v4, s6, v5 bitop3:0xde
	s_mov_b32 s6, 0x1c000
	v_lshlrev_b32_e32 v1, 2, v1
	s_lshl_b32 s2, s4, 13
	s_or_b32 s25, s24, 0x80
	v_bitop3_b32 v4, v4, s6, v5 bitop3:0xde
	v_lshl_or_b32 v142, s4, 6, v1
	s_or_b32 s4, s2, 0x800
	s_or_b32 s6, s2, 0x1000
	s_or_b32 s7, s2, 0x1800
	v_lshl_or_b32 v144, s3, 4, v0
	s_lshr_b32 s3, s25, 1
	v_lshlrev_b32_e32 v10, 6, v195
	s_add_u32 s18, s8, 0x4442000
	v_lshrrev_b32_e32 v9, 2, v252
	v_and_b32_e32 v10, 0x3c0, v10
	s_addc_u32 s19, s22, 0
	s_mov_b32 s15, 0x20000
	v_bitop3_b32 v3, v2, v5, v3 bitop3:0x36
	v_or_b32_e32 v143, s24, v0
	v_and_b32_e32 v9, 4, v9
	v_bitop3_b32 v2, v10, v5, v2 bitop3:0x36
	v_mov_b32_e32 v145, 0x800
	v_or_b32_e32 v147, s3, v0
	s_add_u32 s20, s8, 0x2040000
	v_cndmask_b32_e64 v0, 0, 1, s[0:1]
	s_mov_b32 s14, 0x2200000
	s_mov_b32 s10, 0xc00000
	s_mov_b32 s11, s15
	v_and_or_b32 v146, v1, 4, v145
	v_or_b32_e32 v148, 0x800, v9
	v_or_b32_e32 v149, 0x801, v9
	v_or_b32_e32 v150, 0x802, v9
	v_or_b32_e32 v151, 0x803, v9
	v_add_u32_e32 v152, 0x10000, v138
	v_add_u32_e32 v153, 0x12000, v138
	v_add_u32_e32 v154, 0x14000, v138
	v_add_u32_e32 v155, 0x16000, v138
	s_movk_i32 s26, 0x4000
	v_add_u32_e32 v156, 0x4000, v138
	v_add_u32_e32 v157, 0x6000, v138
	v_add_u32_e32 v158, 0x18000, v138
	v_add_u32_e32 v159, 0x1a000, v138
	v_add_u32_e32 v160, 0x8000, v138
	v_add_u32_e32 v161, 0xa000, v138
	v_add_u32_e32 v162, 0x1c000, v138
	v_add_u32_e32 v163, 0x1e000, v138
	v_add_u32_e32 v164, 0xc000, v138
	v_add_u32_e32 v165, 0xe000, v138
	s_addc_u32 s21, s22, 0
	s_movk_i32 s27, 0xcd
	v_add_u32_e32 v166, s5, v6
	v_add_u32_e32 v167, s2, v3
	v_add_u32_e32 v168, s4, v2
	v_add_u32_e32 v169, s6, v2
	v_add_u32_e32 v170, s7, v2
	v_add_u32_e32 v171, s5, v7
	v_add_u32_e32 v172, s5, v8
	v_add_u32_e32 v173, s5, v4
	s_movk_i32 s28, 0x3080
	v_mov_b32_e32 v129, 0
	s_movk_i32 s29, 0x7cd
	s_movk_i32 s30, 0x7ce
	s_movk_i32 s31, 0x7cf
	s_movk_i32 s34, 0x7dd
	s_movk_i32 s35, 0x7de
	s_movk_i32 s36, 0x7df
	s_movk_i32 s37, 0x7ed
	s_movk_i32 s38, 0x7ee
	s_movk_i32 s39, 0x7ef
	s_movk_i32 s40, 0x7fd
	s_movk_i32 s41, 0x7fe
	s_movk_i32 s42, 0x7ff
	v_cmp_ne_u32_e64 s[2:3], 1, v0
	s_mov_b32 s43, s78
	s_add_u32 s8, s84, 0xc00000
	s_addc_u32 s0, s85, 0
	s_and_b32 s9, s0, 0xffff
	s_mov_b32 s10, 0x400000
	s_add_u32 s12, s84, 0x11262000
	s_addc_u32 s0, s85, 0
	s_and_b32 s13, s0, 0xffff
	s_mov_b32 s14, 0x4400000
	s_add_u32 s18, s84, 0x15662000
	s_addc_u32 s19, s85, 0
	s_mov_b32 s70, s78
	s_cmp_ge_u32 s70, 0x100
	s_cbranch_scc1 .Lq3_skip
;     ...
;   for (int tile0 = rev ? (int)(gridDim.x - 1 - blockIdx.x) : (int)blockIdx.x; tile0 < ntiles * rep; tile0 += gridDim.x) {
;     const int tile = tile0 % ntiles;
;     int mt = tile / NT, nt = tile - mt * NT + nt0;
;     if (EPI == 1 && NT == 8 && mtiles == 64 && gridDim.x == 256) {
;       const int blk = tile & 255, rnd = tile >> 8;
;       mt = rnd * 32 + (blk & 7) * 4 + (blk >> 6);
;       nt = (blk >> 3) & 7;
;     }
;     const int m0 = mt * BM, n0 = nt * BN;
;     const bool skip_mma = (EPI == 2) && (n0 >= 6144) && (wn == 1);
;     if (NH > 0) {
;       for (int idx = tid; idx < BM * NH; idx += NTHR) {
;         int row = idx / NH, h = idx % NH;
;         const float* pp = parts + (size_t)(m0 + row) * 64 + h * (64 / NH);
;         float s = 0.f;
; #pragma unroll
;         for (int q = 0; q < 64 / NH; ++q) s += pp[q];
;         rstdS[idx] = rsqrtf(s / (float)(K / NH) + 1e-6f);
;       }
;     }
;     u32x4 ra[2][4], rb[2][2];
;     const u16* ap = A + (size_t)(m0 + srow) * K + skc * 8;
;     const u16* bp = Bt + (size_t)(n0 + srow) * K + skc * 8;
; #pragma unroll
;     for (int i = 0; i < 4; ++i) ra[0][i] = *(const u32x4*)(ap + (size_t)(64 * i) * K);
; #pragma unroll
;     for (int i = 0; i < 2; ++i) rb[0][i] = *(const u32x4*)(bp + (size_t)(64 * i) * K);
; #pragma unroll
;     for (int i = 0; i < 4; ++i) ra[1][i] = *(const u32x4*)(ap + (size_t)(64 * i) * K + BK);
; #pragma unroll
;     for (int i = 0; i < 2; ++i) rb[1][i] = *(const u32x4*)(bp + (size_t)(64 * i) * K + BK);
;     {
;       unsigned char* base = smem;
; #pragma unroll
;       for (int i = 0; i < 4; ++i) *(u32x4*)(base + (srow + 64 * i) * LR + skc * 16) = ra[0][i];
; #pragma unroll
;       for (int i = 0; i < 2; ++i) *(u32x4*)(base + BM * LR + (srow + 64 * i) * LR + skc * 16) = rb[0][i];
;     }
;     __syncthreads();
.Lq3_tile:
	s_and_b32 s0, s70, 7
	s_lshr_b32 s1, s70, 3
	s_lshl_b32 s4, s0, 3
	s_lshr_b32 s0, s1, 2
	s_add_i32 s4, s4, s0
	s_and_b32 s1, s1, 3
	s_lshl_b32 s5, s4, 20
	s_lshl_b32 s6, s1, 20
	s_mov_b32 s7, s5
	v_writelane_b32 v255, s4, 51
	v_writelane_b32 v255, s1, 52
	v_mov_b32_e32 v200, v252
	v_lshrrev_b32_e32 v201, 2, v200
	v_and_b32_e32 v202, 3, v200
	v_lshl_add_u32 v201, s4, 8, v201
	v_lshlrev_b32_e32 v201, 8, v201
	v_lshl_add_u32 v203, v202, 6, v201
	global_load_dwordx4 v[208:211], v203, s[18:19]
	global_load_dwordx4 v[212:215], v203, s[18:19] offset:16
	global_load_dwordx4 v[216:219], v203, s[18:19] offset:32
	global_load_dwordx4 v[220:223], v203, s[18:19] offset:48
	v_add_u32_e32 v200, 512, v252
	v_lshrrev_b32_e32 v201, 2, v200
	v_and_b32_e32 v202, 3, v200
	v_lshl_add_u32 v201, s4, 8, v201
	v_lshlrev_b32_e32 v201, 8, v201
	v_lshl_add_u32 v204, v202, 6, v201
	global_load_dwordx4 v[224:227], v204, s[18:19]
	global_load_dwordx4 v[228:231], v204, s[18:19] offset:16
	global_load_dwordx4 v[232:235], v204, s[18:19] offset:32
	global_load_dwordx4 v[236:239], v204, s[18:19] offset:48
	v_readfirstlane_b32 s44, v152
	s_nop 1
	s_mov_b32 m0, s44
	s_nop 0
	buffer_load_dwordx4 v139, s[8:11], s6 offen lds
	v_readfirstlane_b32 s44, v153
	s_nop 1
	s_mov_b32 m0, s44
	s_nop 0
	buffer_load_dwordx4 v141, s[8:11], s6 offen lds
	v_readfirstlane_b32 s44, v138
	s_nop 1
	s_mov_b32 m0, s44
	s_nop 0
	buffer_load_dwordx4 v139, s[12:15], s5 offen lds
	v_readfirstlane_b32 s44, v140
	s_nop 1
	s_mov_b32 m0, s44
	s_nop 0
	buffer_load_dwordx4 v141, s[12:15], s5 offen lds
	s_or_b32 s45, s6, 0x80000
	v_readfirstlane_b32 s44, v154
	s_nop 1
	s_mov_b32 m0, s44
	s_nop 0
	buffer_load_dwordx4 v139, s[8:11], s45 offen lds
	v_readfirstlane_b32 s44, v155
	s_nop 1
	s_mov_b32 m0, s44
	s_nop 0
	buffer_load_dwordx4 v141, s[8:11], s45 offen lds
	s_or_b32 s45, s5, 0x80000
	v_readfirstlane_b32 s44, v156
	s_nop 1
	s_mov_b32 m0, s44
	s_nop 0
	buffer_load_dwordx4 v139, s[12:15], s45 offen lds
	v_readfirstlane_b32 s44, v157
	s_nop 1
	s_mov_b32 m0, s44
	s_nop 0
	buffer_load_dwordx4 v141, s[12:15], s45 offen lds
	s_waitcnt vmcnt(8)
	v_add_f32_e32 v200, 0, v208
	v_add_f32_e32 v200, v200, v209
	v_add_f32_e32 v200, v200, v210
	v_add_f32_e32 v200, v200, v211
	v_add_f32_e32 v200, v200, v212
	v_add_f32_e32 v200, v200, v213
	v_add_f32_e32 v200, v200, v214
	v_add_f32_e32 v200, v200, v215
	v_add_f32_e32 v200, v200, v216
	v_add_f32_e32 v200, v200, v217
	v_add_f32_e32 v200, v200, v218
	v_add_f32_e32 v200, v200, v219
	v_add_f32_e32 v200, v200, v220
	v_add_f32_e32 v200, v200, v221
	v_add_f32_e32 v200, v200, v222
	v_add_f32_e32 v200, v200, v223
	v_mov_b32_e32 v201, 0x358637bd
	v_fmac_f32_e32 v201, 0x3b000000, v200
	v_rsq_f32_e32 v201, v201
	v_lshlrev_b32_e32 v202, 2, v252
	v_add_u32_e32 v202, 0x20000, v202
	ds_write_b32 v202, v201
	v_add_f32_e32 v200, 0, v224
	v_add_f32_e32 v200, v200, v225
	v_add_f32_e32 v200, v200, v226
	v_add_f32_e32 v200, v200, v227
	v_add_f32_e32 v200, v200, v228
	v_add_f32_e32 v200, v200, v229
	v_add_f32_e32 v200, v200, v230
	v_add_f32_e32 v200, v200, v231
	v_add_f32_e32 v200, v200, v232
	v_add_f32_e32 v200, v200, v233
	v_add_f32_e32 v200, v200, v234
	v_add_f32_e32 v200, v200, v235
	v_add_f32_e32 v200, v200, v236
	v_add_f32_e32 v200, v200, v237
	v_add_f32_e32 v200, v200, v238
	v_add_f32_e32 v200, v200, v239
	v_mov_b32_e32 v201, 0x358637bd
	v_fmac_f32_e32 v201, 0x3b000000, v200
	v_rsq_f32_e32 v201, v201
	v_lshlrev_b32_e32 v202, 2, v252
	v_add_u32_e32 v202, 0x20800, v202
	ds_write_b32 v202, v201
	v_and_b32_e32 v128, 15, v195
	v_lshrrev_b32_e32 v129, 2, v252
	v_and_b32_e32 v129, 64, v129
	v_add_u32_e32 v128, v128, v129
	v_lshlrev_b32_e32 v128, 4, v128
	v_add_u32_e32 v128, 0x20000, v128
	s_waitcnt lgkmcnt(0)
	s_and_b64 vcc, exec, s[2:3]
	s_cbranch_vccnz .Lq3_201
	s_barrier

;     ...
;       if (NH > 0) {
;         const int per = KT / NH;
;         if (((kt + 1) % per) == 0) {
;           const int h = (kt + 1) / per - 1;
; #pragma unroll
;           for (int mf = 0; mf < 4; ++mf)
; #pragma unroll
;             for (int r = 0; r < 4; ++r) {
;               float s = rstdS[(wm * 64 + mf * 16 + 4 * g + r) * NH + h];
; #pragma unroll
;               for (int nf = 0; nf < 4; ++nf) {
;                 accT[mf][nf][r] += s * acc[mf][nf][r];
;                 acc[mf][nf][r] = 0.f;
;               }
;             }
;         }
;     ...
; #pragma unroll
;     for (int mf = 0; mf < 4; ++mf) {
;       __builtin_amdgcn_sched_barrier(0);
;       float rvv[4][4];
;       if (EPI == 1) {
; #pragma unroll
;         for (int r = 0; r < 4; ++r) {
;           const int row = m0 + wm * 64 + mf * 16 + 4 * g + r;
; #pragma unroll
;           for (int nf = 0; nf < 4; ++nf) {
;             const int col = n0 + wn * 64 + nf * 16 + l15;
;             rvv[r][nf] = resid ? resid[(size_t)row * 1024 + col] : xrow(p, row)[col];
;           }
;         }
;       }
.Lq3_205:
	v_add_u32_e32 v220, 12, v128
	ds_read_b32 v221, v220
	ds_read_b32 v223, v220 offset:256
	ds_read_b32 v225, v220 offset:512
	ds_read_b32 v227, v220 offset:768
	ds_read_b32 v229, v220 offset:2048
	ds_read_b32 v231, v220 offset:2304
	ds_read_b32 v233, v220 offset:2560
	ds_read_b32 v235, v220 offset:2816
	s_waitcnt lgkmcnt(0)
	s_nop 7
	v_mul_f32_e32 v120, v221, v120
	v_mul_f32_e32 v121, v221, v121
	v_mul_f32_e32 v122, v221, v122
	v_mul_f32_e32 v123, v221, v123
	v_mul_f32_e32 v124, v221, v124
	v_mul_f32_e32 v125, v221, v125
	v_mul_f32_e32 v126, v221, v126
	v_mul_f32_e32 v127, v221, v127
	v_mul_f32_e32 v112, v221, v112
	v_mul_f32_e32 v113, v221, v113
	v_mul_f32_e32 v114, v221, v114
	v_mul_f32_e32 v115, v221, v115
	v_mul_f32_e32 v116, v221, v116
	v_mul_f32_e32 v117, v221, v117
	v_mul_f32_e32 v118, v221, v118
	v_mul_f32_e32 v119, v221, v119
	v_mul_f32_e32 v104, v223, v104
	v_mul_f32_e32 v105, v223, v105
	v_mul_f32_e32 v106, v223, v106
	v_mul_f32_e32 v107, v223, v107
	v_mul_f32_e32 v108, v223, v108
	v_mul_f32_e32 v109, v223, v109
	v_mul_f32_e32 v110, v223, v110
	v_mul_f32_e32 v111, v223, v111
	v_mul_f32_e32 v96, v223, v96
	v_mul_f32_e32 v97, v223, v97
	v_mul_f32_e32 v98, v223, v98
	v_mul_f32_e32 v99, v223, v99
	v_mul_f32_e32 v100, v223, v100
	v_mul_f32_e32 v101, v223, v101
	v_mul_f32_e32 v102, v223, v102
	v_mul_f32_e32 v103, v223, v103
	v_mul_f32_e32 v88, v225, v88
	v_mul_f32_e32 v89, v225, v89
	v_mul_f32_e32 v90, v225, v90
	v_mul_f32_e32 v91, v225, v91
	v_mul_f32_e32 v92, v225, v92
	v_mul_f32_e32 v93, v225, v93
	v_mul_f32_e32 v94, v225, v94
	v_mul_f32_e32 v95, v225, v95
	v_mul_f32_e32 v80, v225, v80
	v_mul_f32_e32 v81, v225, v81
	v_mul_f32_e32 v82, v225, v82
	v_mul_f32_e32 v83, v225, v83
	v_mul_f32_e32 v84, v225, v84
	v_mul_f32_e32 v85, v225, v85
	v_mul_f32_e32 v86, v225, v86
	v_mul_f32_e32 v87, v225, v87
	v_mul_f32_e32 v72, v227, v72
	v_mul_f32_e32 v73, v227, v73
	v_mul_f32_e32 v74, v227, v74
	v_mul_f32_e32 v75, v227, v75
	v_mul_f32_e32 v76, v227, v76
	v_mul_f32_e32 v77, v227, v77
	v_mul_f32_e32 v78, v227, v78
	v_mul_f32_e32 v79, v227, v79
	v_mul_f32_e32 v64, v227, v64
	v_mul_f32_e32 v65, v227, v65
	v_mul_f32_e32 v66, v227, v66
	v_mul_f32_e32 v67, v227, v67
	v_mul_f32_e32 v68, v227, v68
	v_mul_f32_e32 v69, v227, v69
	v_mul_f32_e32 v70, v227, v70
	v_mul_f32_e32 v71, v227, v71
	v_mul_f32_e32 v56, v229, v56
	v_mul_f32_e32 v57, v229, v57
	v_mul_f32_e32 v58, v229, v58
	v_mul_f32_e32 v59, v229, v59
	v_mul_f32_e32 v60, v229, v60
	v_mul_f32_e32 v61, v229, v61
	v_mul_f32_e32 v62, v229, v62
	v_mul_f32_e32 v63, v229, v63
	v_mul_f32_e32 v48, v229, v48
	v_mul_f32_e32 v49, v229, v49
	v_mul_f32_e32 v50, v229, v50
	v_mul_f32_e32 v51, v229, v51
	v_mul_f32_e32 v52, v229, v52
	v_mul_f32_e32 v53, v229, v53
	v_mul_f32_e32 v54, v229, v54
	v_mul_f32_e32 v55, v229, v55
	v_mul_f32_e32 v40, v231, v40
	v_mul_f32_e32 v41, v231, v41
	v_mul_f32_e32 v42, v231, v42
	v_mul_f32_e32 v43, v231, v43
	v_mul_f32_e32 v44, v231, v44
	v_mul_f32_e32 v45, v231, v45
	v_mul_f32_e32 v46, v231, v46
	v_mul_f32_e32 v47, v231, v47
	v_mul_f32_e32 v32, v231, v32
	v_mul_f32_e32 v33, v231, v33
	v_mul_f32_e32 v34, v231, v34
	v_mul_f32_e32 v35, v231, v35
	v_mul_f32_e32 v36, v231, v36
	v_mul_f32_e32 v37, v231, v37
	v_mul_f32_e32 v38, v231, v38
	v_mul_f32_e32 v39, v231, v39
	v_mul_f32_e32 v24, v233, v24
	v_mul_f32_e32 v25, v233, v25
	v_mul_f32_e32 v26, v233, v26
	v_mul_f32_e32 v27, v233, v27
	v_mul_f32_e32 v28, v233, v28
	v_mul_f32_e32 v29, v233, v29
	v_mul_f32_e32 v30, v233, v30
	v_mul_f32_e32 v31, v233, v31
	v_mul_f32_e32 v16, v233, v16
	v_mul_f32_e32 v17, v233, v17
	v_mul_f32_e32 v18, v233, v18
	v_mul_f32_e32 v19, v233, v19
	v_mul_f32_e32 v20, v233, v20
	v_mul_f32_e32 v21, v233, v21
	v_mul_f32_e32 v22, v233, v22
	v_mul_f32_e32 v23, v233, v23
	v_mul_f32_e32 v8, v235, v8
	v_mul_f32_e32 v9, v235, v9
	v_mul_f32_e32 v10, v235, v10
	v_mul_f32_e32 v11, v235, v11
	v_mul_f32_e32 v12, v235, v12
	v_mul_f32_e32 v13, v235, v13
	v_mul_f32_e32 v14, v235, v14
	v_mul_f32_e32 v15, v235, v15
	v_mul_f32_e32 v0, v235, v0
	v_mul_f32_e32 v1, v235, v1
	v_mul_f32_e32 v2, v235, v2
	v_mul_f32_e32 v3, v235, v3
	v_mul_f32_e32 v4, v235, v4
	v_mul_f32_e32 v5, v235, v5
	v_mul_f32_e32 v6, v235, v6
	v_mul_f32_e32 v7, v235, v7
	s_barrier
	v_readlane_b32 s4, v255, 51
	v_readlane_b32 s1, v255, 52
	v_readlane_b32 s5, v255, 6
	v_and_b32_e32 v176, 15, v195
	v_lshrrev_b32_e32 v177, 4, v195
	s_lshr_b32 s6, s5, 2
	s_and_b32 s7, s5, 3
	s_lshl_b32 s6, s6, 6
	v_add_u32_e32 v178, s6, v176
	v_mul_u32_u24_e32 v178, 0x410, v178
	s_lshl_b32 s7, s7, 7
	v_lshl_add_u32 v178, v177, 4, v178
	v_add_u32_e32 v178, s7, v178
	s_lshl_b32 s7, s5, 4
	v_lshlrev_b32_e32 v179, 4, v195
	s_mul_i32 s6, s7, 0x410
	v_add_u32_e32 v180, s6, v179
	s_lshl_b32 s4, s4, 8
	s_add_i32 s4, s4, s7
	s_lshl_b32 s4, s4, 12
	s_lshl_b32 s1, s1, 10
	s_add_i32 s4, s4, s1
	v_add_u32_e32 v181, s4, v179
	v_readlane_b32 s0, v255, 0
	v_readlane_b32 s1, v255, 1
	s_load_dwordx2 s[20:21], s[0:1], 0x0
	s_add_u32 s24, s84, 0x15aa2000
	s_addc_u32 s25, s85, 0
	s_waitcnt lgkmcnt(0)
	v_mov_b32_e32 v182, v181
	global_load_dwordx4 v[184:187], v182, s[20:21]
	v_add_u32_e32 v182, 0x1000, v182
	global_load_dwordx4 v[188:191], v182, s[20:21]
	v_add_u32_e32 v182, 0x1000, v182
	global_load_dwordx4 v[196:199], v182, s[20:21]
	v_add_u32_e32 v182, 0x1000, v182
	global_load_dwordx4 v[200:203], v182, s[20:21]
	v_add_u32_e32 v182, 0x1000, v182
	global_load_dwordx4 v[204:207], v182, s[20:21]
	v_add_u32_e32 v182, 0x1000, v182
	global_load_dwordx4 v[208:211], v182, s[20:21]
	v_add_u32_e32 v182, 0x1000, v182
	global_load_dwordx4 v[212:215], v182, s[20:21]
	v_add_u32_e32 v182, 0x1000, v182
	global_load_dwordx4 v[216:219], v182, s[20:21]
	v_add_u32_e32 v182, 0x1000, v182
	global_load_dwordx4 v[220:223], v182, s[20:21]
	v_add_u32_e32 v182, 0x1000, v182
	global_load_dwordx4 v[224:227], v182, s[20:21]
	v_add_u32_e32 v182, 0x1000, v182
	global_load_dwordx4 v[228:231], v182, s[20:21]
	v_add_u32_e32 v182, 0x1000, v182
	global_load_dwordx4 v[232:235], v182, s[20:21]
	v_add_u32_e32 v182, 0x1000, v182
	global_load_dwordx4 v[236:239], v182, s[20:21]
	v_add_u32_e32 v182, 0x1000, v182
	global_load_dwordx4 v[240:243], v182, s[20:21]
	v_add_u32_e32 v182, 0x1000, v182
	global_load_dwordx4 v[244:247], v182, s[20:21]
	v_add_u32_e32 v182, 0x1000, v182
	global_load_dwordx4 v[248:251], v182, s[20:21]
	ds_write_b128 v178, v[120:123]
	ds_write_b128 v178, v[124:127] offset:64
	ds_write_b128 v178, v[104:107] offset:16640
	ds_write_b128 v178, v[108:111] offset:16704
	ds_write_b128 v178, v[88:91] offset:33280
	ds_write_b128 v178, v[92:95] offset:33344
	ds_write_b128 v178, v[72:75] offset:49920
	ds_write_b128 v178, v[76:79] offset:49984
	ds_write_b128 v178, v[112:115] offset:512
	ds_write_b128 v178, v[116:119] offset:576
	ds_write_b128 v178, v[96:99] offset:17152
	ds_write_b128 v178, v[100:103] offset:17216
	ds_write_b128 v178, v[80:83] offset:33792
	ds_write_b128 v178, v[84:87] offset:33856
	ds_write_b128 v178, v[64:67] offset:50432
	ds_write_b128 v178, v[68:71] offset:50496
	s_waitcnt lgkmcnt(0)
	s_barrier
;     ...
;       if (EPI == 1) {
; #pragma unroll
;         for (int r = 0; r < 4; ++r) {
;           const int row = m0 + wm * 64 + mf * 16 + 4 * g + r;
; #pragma unroll
;           for (int nf = 0; nf < 4; ++nf) {
;             const int col = n0 + wn * 64 + nf * 16 + l15;
;             rvv[r][nf] = resid ? resid[(size_t)row * 1024 + col] : xrow(p, row)[col];
;           }
;         }
;       }
; #pragma unroll
;       for (int r = 0; r < 4; ++r) {
;         const int row = m0 + wm * 64 + mf * 16 + 4 * g + r;
;         if (EPI == 0) {
;           u16* proj = (u16*)(p.ws + OFF_PROJ) + (size_t)row * PROJ_LD;
;           if (n0 < 2048) {
;             const float2* rope = (const float2*)(p.ws + OFF_ROPE);
;             const int pi = row < NPROMPT ? (row & 2047) : 2048 + ((row - NPROMPT) & 7);
; #pragma unroll
;             for (int np = 0; np < 2; ++np) {
;               const int pc = n0 + wn * 64 + np * 32;
;               const int i = ((pc & 255) >> 5) * 16 + l15;
;               const float2 cs = rope[pi * 128 + i];
;               const float x1 = acc[mf][2 * np][r], x2 = acc[mf][2 * np + 1][r];
;               float y1 = x1 * cs.x - x2 * cs.y, y2 = x1 * cs.y + x2 * cs.x;
;               if (pc >= 1024) { y1 *= 0.0625f; y2 *= 0.0625f; }
;               const int f1 = (pc & ~255) + i;
;               proj[f1] = f2bf(y1);
;               proj[f1 + 128] = f2bf(y2);
;             }
;           } else {
; #pragma unroll
;             for (int nf = 0; nf < 4; ++nf) proj[n0 + wn * 64 + nf * 16 + l15] = f2bf(acc[mf][nf][r]);
;           }
;         } else if (EPI == 1) {
; #pragma unroll
;           for (int nf = 0; nf < 4; ++nf) {
;             const int col = n0 + wn * 64 + nf * 16 + l15;
;             const float a = (NH > 0) ? accT[mf][nf][r] : acc[mf][nf][r];
;             outf[(size_t)row * 1024 + col] = rvv[r][nf] + a;
;           }
	ds_read_b128 v[64:67], v180
	ds_read_b128 v[68:71], v180 offset:1040
	ds_read_b128 v[72:75], v180 offset:2080
	ds_read_b128 v[76:79], v180 offset:3120
	ds_read_b128 v[80:83], v180 offset:4160
	ds_read_b128 v[84:87], v180 offset:5200
	ds_read_b128 v[88:91], v180 offset:6240
	ds_read_b128 v[92:95], v180 offset:7280
	ds_read_b128 v[96:99], v180 offset:8320
	ds_read_b128 v[100:103], v180 offset:9360
	ds_read_b128 v[104:107], v180 offset:10400
	ds_read_b128 v[108:111], v180 offset:11440
	ds_read_b128 v[112:115], v180 offset:12480
	ds_read_b128 v[116:119], v180 offset:13520
	ds_read_b128 v[120:123], v180 offset:14560
	ds_read_b128 v[124:127], v180 offset:15600
	s_waitcnt lgkmcnt(0)
	s_barrier
	v_mov_b32_e32 v182, v181
	s_waitcnt vmcnt(15)
	v_add_f32_e32 v64, v64, v184
	v_add_f32_e32 v65, v65, v185
	v_add_f32_e32 v66, v66, v186
	v_add_f32_e32 v67, v67, v187
	global_store_dwordx4 v182, v[64:67], s[24:25]
	v_add_u32_e32 v182, 0x1000, v182
	s_waitcnt vmcnt(15)
	v_add_f32_e32 v68, v68, v188
	v_add_f32_e32 v69, v69, v189
	v_add_f32_e32 v70, v70, v190
	v_add_f32_e32 v71, v71, v191
	global_store_dwordx4 v182, v[68:71], s[24:25]
	v_add_u32_e32 v182, 0x1000, v182
	s_waitcnt vmcnt(15)
	v_add_f32_e32 v72, v72, v196
	v_add_f32_e32 v73, v73, v197
	v_add_f32_e32 v74, v74, v198
	v_add_f32_e32 v75, v75, v199
	global_store_dwordx4 v182, v[72:75], s[24:25]
	v_add_u32_e32 v182, 0x1000, v182
	s_waitcnt vmcnt(15)
	v_add_f32_e32 v76, v76, v200
	v_add_f32_e32 v77, v77, v201
	v_add_f32_e32 v78, v78, v202
	v_add_f32_e32 v79, v79, v203
	global_store_dwordx4 v182, v[76:79], s[24:25]
	v_add_u32_e32 v182, 0x1000, v182
	s_waitcnt vmcnt(15)
	v_add_f32_e32 v80, v80, v204
	v_add_f32_e32 v81, v81, v205
	v_add_f32_e32 v82, v82, v206
	v_add_f32_e32 v83, v83, v207
	global_store_dwordx4 v182, v[80:83], s[24:25]
	v_add_u32_e32 v182, 0x1000, v182
	s_waitcnt vmcnt(15)
	v_add_f32_e32 v84, v84, v208
	v_add_f32_e32 v85, v85, v209
	v_add_f32_e32 v86, v86, v210
	v_add_f32_e32 v87, v87, v211
	global_store_dwordx4 v182, v[84:87], s[24:25]
	v_add_u32_e32 v182, 0x1000, v182
	s_waitcnt vmcnt(15)
	v_add_f32_e32 v88, v88, v212
	v_add_f32_e32 v89, v89, v213
	v_add_f32_e32 v90, v90, v214
	v_add_f32_e32 v91, v91, v215
	global_store_dwordx4 v182, v[88:91], s[24:25]
	v_add_u32_e32 v182, 0x1000, v182
	s_waitcnt vmcnt(15)
	v_add_f32_e32 v92, v92, v216
	v_add_f32_e32 v93, v93, v217
	v_add_f32_e32 v94, v94, v218
	v_add_f32_e32 v95, v95, v219
	global_store_dwordx4 v182, v[92:95], s[24:25]
	v_add_u32_e32 v182, 0x1000, v182
	s_waitcnt vmcnt(15)
	v_add_f32_e32 v96, v96, v220
	v_add_f32_e32 v97, v97, v221
	v_add_f32_e32 v98, v98, v222
	v_add_f32_e32 v99, v99, v223
	global_store_dwordx4 v182, v[96:99], s[24:25]
	v_add_u32_e32 v182, 0x1000, v182
	s_waitcnt vmcnt(15)
	v_add_f32_e32 v100, v100, v224
	v_add_f32_e32 v101, v101, v225
	v_add_f32_e32 v102, v102, v226
	v_add_f32_e32 v103, v103, v227
	global_store_dwordx4 v182, v[100:103], s[24:25]
	v_add_u32_e32 v182, 0x1000, v182
	s_waitcnt vmcnt(15)
	v_add_f32_e32 v104, v104, v228
	v_add_f32_e32 v105, v105, v229
	v_add_f32_e32 v106, v106, v230
	v_add_f32_e32 v107, v107, v231
	global_store_dwordx4 v182, v[104:107], s[24:25]
	v_add_u32_e32 v182, 0x1000, v182
	s_waitcnt vmcnt(15)
	v_add_f32_e32 v108, v108, v232
	v_add_f32_e32 v109, v109, v233
	v_add_f32_e32 v110, v110, v234
	v_add_f32_e32 v111, v111, v235
	global_store_dwordx4 v182, v[108:111], s[24:25]
	v_add_u32_e32 v182, 0x1000, v182
	s_waitcnt vmcnt(15)
	v_add_f32_e32 v112, v112, v236
	v_add_f32_e32 v113, v113, v237
	v_add_f32_e32 v114, v114, v238
	v_add_f32_e32 v115, v115, v239
	global_store_dwordx4 v182, v[112:115], s[24:25]
	v_add_u32_e32 v182, 0x1000, v182
	s_waitcnt vmcnt(15)
	v_add_f32_e32 v116, v116, v240
	v_add_f32_e32 v117, v117, v241
	v_add_f32_e32 v118, v118, v242
	v_add_f32_e32 v119, v119, v243
	global_store_dwordx4 v182, v[116:119], s[24:25]
	v_add_u32_e32 v182, 0x1000, v182
	s_waitcnt vmcnt(15)
	v_add_f32_e32 v120, v120, v244
	v_add_f32_e32 v121, v121, v245
	v_add_f32_e32 v122, v122, v246
	v_add_f32_e32 v123, v123, v247
	global_store_dwordx4 v182, v[120:123], s[24:25]
	v_add_u32_e32 v182, 0x1000, v182
	s_waitcnt vmcnt(15)
	v_add_f32_e32 v124, v124, v248
	v_add_f32_e32 v125, v125, v249
	v_add_f32_e32 v126, v126, v250
	v_add_f32_e32 v127, v127, v251
	global_store_dwordx4 v182, v[124:127], s[24:25]
	v_add_u32_e32 v181, 0x80000, v181
	v_mov_b32_e32 v182, v181
	global_load_dwordx4 v[184:187], v182, s[20:21]
	v_add_u32_e32 v182, 0x1000, v182
	global_load_dwordx4 v[188:191], v182, s[20:21]
	v_add_u32_e32 v182, 0x1000, v182
	global_load_dwordx4 v[196:199], v182, s[20:21]
	v_add_u32_e32 v182, 0x1000, v182
	global_load_dwordx4 v[200:203], v182, s[20:21]
	v_add_u32_e32 v182, 0x1000, v182
	global_load_dwordx4 v[204:207], v182, s[20:21]
	v_add_u32_e32 v182, 0x1000, v182
	global_load_dwordx4 v[208:211], v182, s[20:21]
	v_add_u32_e32 v182, 0x1000, v182
	global_load_dwordx4 v[212:215], v182, s[20:21]
	v_add_u32_e32 v182, 0x1000, v182
	global_load_dwordx4 v[216:219], v182, s[20:21]
	v_add_u32_e32 v182, 0x1000, v182
	global_load_dwordx4 v[220:223], v182, s[20:21]
	v_add_u32_e32 v182, 0x1000, v182
	global_load_dwordx4 v[224:227], v182, s[20:21]
	v_add_u32_e32 v182, 0x1000, v182
	global_load_dwordx4 v[228:231], v182, s[20:21]
	v_add_u32_e32 v182, 0x1000, v182
	global_load_dwordx4 v[232:235], v182, s[20:21]
	v_add_u32_e32 v182, 0x1000, v182
	global_load_dwordx4 v[236:239], v182, s[20:21]
	v_add_u32_e32 v182, 0x1000, v182
	global_load_dwordx4 v[240:243], v182, s[20:21]
	v_add_u32_e32 v182, 0x1000, v182
	global_load_dwordx4 v[244:247], v182, s[20:21]
	v_add_u32_e32 v182, 0x1000, v182
	global_load_dwordx4 v[248:251], v182, s[20:21]
	ds_write_b128 v178, v[56:59]
	ds_write_b128 v178, v[60:63] offset:64
	ds_write_b128 v178, v[40:43] offset:16640
	ds_write_b128 v178, v[44:47] offset:16704
	ds_write_b128 v178, v[24:27] offset:33280
	ds_write_b128 v178, v[28:31] offset:33344
	ds_write_b128 v178, v[8:11] offset:49920
	ds_write_b128 v178, v[12:15] offset:49984
	ds_write_b128 v178, v[48:51] offset:512
	ds_write_b128 v178, v[52:55] offset:576
	ds_write_b128 v178, v[32:35] offset:17152
	ds_write_b128 v178, v[36:39] offset:17216
	ds_write_b128 v178, v[16:19] offset:33792
	ds_write_b128 v178, v[20:23] offset:33856
	ds_write_b128 v178, v[0:3] offset:50432
	ds_write_b128 v178, v[4:7] offset:50496
	s_waitcnt lgkmcnt(0)
	s_barrier
;     ...
;         } else if (EPI == 1) {
; #pragma unroll
;           for (int nf = 0; nf < 4; ++nf) {
;             const int col = n0 + wn * 64 + nf * 16 + l15;
;             const float a = (NH > 0) ? accT[mf][nf][r] : acc[mf][nf][r];
;             outf[(size_t)row * 1024 + col] = rvv[r][nf] + a;
;           }
; template <int NH>
; __device__ void gemm_sample_rows(const Params& p, const u16* __restrict__ A, const u16* __restrict__ Bt,
;                                  const float* __restrict__ resid, float* __restrict__ outf, unsigned char* smem, const int rep) {
;   constexpr int K = 2048, RS = 65;
;   float* red = (float*)smem;
;   float* rstdS = red + 8 * 64 * RS;
;   const int tid = (int)p.tidx, lane = tid & 63, w = (int)p.wv, l15 = lane & 15, g = lane >> 4;
;   const float* parts = (const float*)(p.ws + OFF_PARTS);
;   for (int item0 = blockIdx.x; item0 < 256 * rep; item0 += gridDim.x) {
;     const int item = item0 & 255;
;     const int m0 = NPROMPT + (item >> 4) * 64, n0 = (item & 15) * 64;
;     for (int idx = tid; idx < 64 * NH; idx += NTHR) {
	ds_read_b128 v[64:67], v180
	ds_read_b128 v[68:71], v180 offset:1040
	ds_read_b128 v[72:75], v180 offset:2080
	ds_read_b128 v[76:79], v180 offset:3120
	ds_read_b128 v[80:83], v180 offset:4160
	ds_read_b128 v[84:87], v180 offset:5200
	ds_read_b128 v[88:91], v180 offset:6240
	ds_read_b128 v[92:95], v180 offset:7280
	ds_read_b128 v[96:99], v180 offset:8320
	ds_read_b128 v[100:103], v180 offset:9360
	ds_read_b128 v[104:107], v180 offset:10400
	ds_read_b128 v[108:111], v180 offset:11440
	ds_read_b128 v[112:115], v180 offset:12480
	ds_read_b128 v[116:119], v180 offset:13520
	ds_read_b128 v[120:123], v180 offset:14560
	ds_read_b128 v[124:127], v180 offset:15600
	s_waitcnt lgkmcnt(0)
	s_barrier
	v_mov_b32_e32 v182, v181
	s_waitcnt vmcnt(15)
	v_add_f32_e32 v64, v64, v184
	v_add_f32_e32 v65, v65, v185
	v_add_f32_e32 v66, v66, v186
	v_add_f32_e32 v67, v67, v187
	global_store_dwordx4 v182, v[64:67], s[24:25]
	v_add_u32_e32 v182, 0x1000, v182
	s_waitcnt vmcnt(15)
	v_add_f32_e32 v68, v68, v188
	v_add_f32_e32 v69, v69, v189
	v_add_f32_e32 v70, v70, v190
	v_add_f32_e32 v71, v71, v191
	global_store_dwordx4 v182, v[68:71], s[24:25]
	v_add_u32_e32 v182, 0x1000, v182
	s_waitcnt vmcnt(15)
	v_add_f32_e32 v72, v72, v196
	v_add_f32_e32 v73, v73, v197
	v_add_f32_e32 v74, v74, v198
	v_add_f32_e32 v75, v75, v199
	global_store_dwordx4 v182, v[72:75], s[24:25]
	v_add_u32_e32 v182, 0x1000, v182
	s_waitcnt vmcnt(15)
	v_add_f32_e32 v76, v76, v200
	v_add_f32_e32 v77, v77, v201
	v_add_f32_e32 v78, v78, v202
	v_add_f32_e32 v79, v79, v203
	global_store_dwordx4 v182, v[76:79], s[24:25]
	v_add_u32_e32 v182, 0x1000, v182
	s_waitcnt vmcnt(15)
	v_add_f32_e32 v80, v80, v204
	v_add_f32_e32 v81, v81, v205
	v_add_f32_e32 v82, v82, v206
	v_add_f32_e32 v83, v83, v207
	global_store_dwordx4 v182, v[80:83], s[24:25]
	v_add_u32_e32 v182, 0x1000, v182
	s_waitcnt vmcnt(15)
	v_add_f32_e32 v84, v84, v208
	v_add_f32_e32 v85, v85, v209
	v_add_f32_e32 v86, v86, v210
	v_add_f32_e32 v87, v87, v211
	global_store_dwordx4 v182, v[84:87], s[24:25]
	v_add_u32_e32 v182, 0x1000, v182
	s_waitcnt vmcnt(15)
	v_add_f32_e32 v88, v88, v212
	v_add_f32_e32 v89, v89, v213
	v_add_f32_e32 v90, v90, v214
	v_add_f32_e32 v91, v91, v215
	global_store_dwordx4 v182, v[88:91], s[24:25]
	v_add_u32_e32 v182, 0x1000, v182
	s_waitcnt vmcnt(15)
	v_add_f32_e32 v92, v92, v216
	v_add_f32_e32 v93, v93, v217
	v_add_f32_e32 v94, v94, v218
	v_add_f32_e32 v95, v95, v219
	global_store_dwordx4 v182, v[92:95], s[24:25]
	v_add_u32_e32 v182, 0x1000, v182
	s_waitcnt vmcnt(15)
	v_add_f32_e32 v96, v96, v220
	v_add_f32_e32 v97, v97, v221
	v_add_f32_e32 v98, v98, v222
	v_add_f32_e32 v99, v99, v223
	global_store_dwordx4 v182, v[96:99], s[24:25]
	v_add_u32_e32 v182, 0x1000, v182
	s_waitcnt vmcnt(15)
	v_add_f32_e32 v100, v100, v224
	v_add_f32_e32 v101, v101, v225
	v_add_f32_e32 v102, v102, v226
	v_add_f32_e32 v103, v103, v227
	global_store_dwordx4 v182, v[100:103], s[24:25]
	v_add_u32_e32 v182, 0x1000, v182
	s_waitcnt vmcnt(15)
	v_add_f32_e32 v104, v104, v228
	v_add_f32_e32 v105, v105, v229
	v_add_f32_e32 v106, v106, v230
	v_add_f32_e32 v107, v107, v231
	global_store_dwordx4 v182, v[104:107], s[24:25]
	v_add_u32_e32 v182, 0x1000, v182
	s_waitcnt vmcnt(15)
	v_add_f32_e32 v108, v108, v232
	v_add_f32_e32 v109, v109, v233
	v_add_f32_e32 v110, v110, v234
	v_add_f32_e32 v111, v111, v235
	global_store_dwordx4 v182, v[108:111], s[24:25]
	v_add_u32_e32 v182, 0x1000, v182
	s_waitcnt vmcnt(15)
	v_add_f32_e32 v112, v112, v236
	v_add_f32_e32 v113, v113, v237
	v_add_f32_e32 v114, v114, v238
	v_add_f32_e32 v115, v115, v239
	global_store_dwordx4 v182, v[112:115], s[24:25]
	v_add_u32_e32 v182, 0x1000, v182
	s_waitcnt vmcnt(15)
	v_add_f32_e32 v116, v116, v240
	v_add_f32_e32 v117, v117, v241
	v_add_f32_e32 v118, v118, v242
	v_add_f32_e32 v119, v119, v243
	global_store_dwordx4 v182, v[116:119], s[24:25]
	v_add_u32_e32 v182, 0x1000, v182
	s_waitcnt vmcnt(15)
	v_add_f32_e32 v120, v120, v244
	v_add_f32_e32 v121, v121, v245
	v_add_f32_e32 v122, v122, v246
	v_add_f32_e32 v123, v123, v247
	global_store_dwordx4 v182, v[120:123], s[24:25]
	v_add_u32_e32 v182, 0x1000, v182
	s_waitcnt vmcnt(15)
	v_add_f32_e32 v124, v124, v248
	v_add_f32_e32 v125, v125, v249
	v_add_f32_e32 v126, v126, v250
	v_add_f32_e32 v127, v127, v251
	global_store_dwordx4 v182, v[124:127], s[24:25]
	s_waitcnt vmcnt(0)
	s_barrier
	s_add_i32 s70, s70, s96
	s_cmp_lt_u32 s70, 0x100
	s_cbranch_scc1 .Lq3_tile
.Lq3_skip:
	v_readlane_b32 s0, v255, 0
	v_readlane_b32 s1, v255, 1
	s_load_dwordx4 s[8:11], s[0:1], 0x0
	s_mov_b64 s[0:1], 0
	s_add_u32 s14, s84, s0
	s_addc_u32 s15, s85, s1
	v_readlane_b32 s23, v255, 6
	s_bfe_u32 s24, s90, 0x10003
	s_lshl_b32 s22, s23, 6
	s_add_i32 s24, s24, 1
	s_add_u32 s6, s14, 0x15aa2000
	s_addc_u32 s7, s15, 0
	s_waitcnt vmcnt(1)
	v_mbcnt_lo_u32_b32 v0, -1, 0
	s_add_u32 s12, s14, 0x15662000
	v_mbcnt_hi_u32_b32 v195, -1, v0
	s_addc_u32 s13, s15, 0
	s_lshl_b32 s25, s24, 9
	s_mov_b32 s25, 0
	s_mov_b64 s[2:3], 0
	v_add_u32_e32 v196, s22, v195
	s_cmp_lt_i32 s78, s25
	v_and_b32_e32 v181, 15, v195
	s_cbranch_scc1 .LBB0_703
	v_and_b32_e32 v0, 15, v195
	s_branch .LBB0_704

;   constexpr int BM = 256, BN = 128, BK = 64, LR = 144;
;   constexpr int BUFB = (BM + BN) * LR;
;   float* rstdS = (float*)(smem + 2 * BUFB);
;   const int tid = (int)p.tidx, lane = tid & 63, w = (int)p.wv;
;   const int wm = w >> 1, wn = w & 1, l15 = lane & 15, g = lane >> 4;
;   const int KT = K / BK;
;   const int ntiles = mtiles * NT;
;   const float* parts = (const float*)(p.ws + OFF_PARTS);
;   const int srow = tid >> 3, skc = tid & 7;
;   for (int tile0 = rev ? (int)(gridDim.x - 1 - blockIdx.x) : (int)blockIdx.x; tile0 < ntiles * rep; tile0 += gridDim.x) {
;     const int tile = tile0 % ntiles;
;     int mt = tile / NT, nt = tile - mt * NT + nt0;
; template <int EPI>
; __device__ void gemm8_phase(const Params& p, const u16* __restrict__ A, const u16* __restrict__ Bt, const int K, const int nN,
;                             unsigned char* smem, const int rep) {
;     ...
;   const int nM = T_TOK / BM8, nwg = nM * nN;
;   const int wid = (int)p.wv, lane = (int)p.tidx & 63, wr = wid >> 2, wc = wid & 3, fr = lane & 15, fq = lane >> 4;
;   const int nt = K / BK8;
;   const __amdgpu_buffer_rsrc_t rsrc_A = __builtin_amdgcn_make_buffer_rsrc((void*)A, (short)0, T_TOK * K * 2, 0x00020000);
;   const __amdgpu_buffer_rsrc_t rsrc_Bt = __builtin_amdgcn_make_buffer_rsrc((void*)Bt, (short)0, nN * 256 * K * 2, 0x00020000);
;   int voff0, voff1;
;   {
;     int r_, c_;
;     stage_rc((int)p.tidx * 16, r_, c_);
;     voff0 = (r_ * K + c_) * 2;
;     stage_rc((int)p.tidx * 16 + 8192, r_, c_);
;     voff1 = (r_ * K + c_) * 2;
;   }
.LBB0_2005:
	s_cmp_lt_i32 s86, 9
	s_cselect_b64 s[0:1], -1, 0
	s_cmp_gt_i32 s88, 7
	s_cselect_b64 s[2:3], -1, 0
	s_and_b64 s[0:1], s[0:1], s[2:3]
	s_andn2_b64 vcc, exec, s[0:1]
	s_cbranch_vccnz .LBB0_2196
	s_mov_b32 s8, s84
	s_mov_b32 s22, s85
	v_mbcnt_lo_u32_b32 v0, -1, 0
	v_readlane_b32 s2, v255, 6
	v_mbcnt_hi_u32_b32 v195, -1, v0
	s_nop 0
	v_lshl_add_u32 v252, s2, 6, v195
	v_bfe_i32 v1, v252, 27, 1
	v_lshlrev_b32_e32 v138, 4, v252
	v_lshrrev_b32_e32 v1, 22, v1
	v_add_u32_e32 v1, v138, v1
	v_and_b32_e32 v1, 0xfffffc00, v1
	v_sub_u32_e32 v1, v138, v1
	v_lshrrev_b32_e32 v2, 4, v1
	v_bitop3_b32 v1, v2, v1, 32 bitop3:0x6c
	v_ashrrev_i32_e32 v0, 31, v252
	v_ashrrev_i32_e32 v3, 31, v1
	v_lshrrev_b32_e32 v0, 26, v0
	v_lshrrev_b32_e32 v3, 26, v3
	v_add_u32_e32 v0, v252, v0
	v_add_u32_e32 v3, v1, v3
	v_ashrrev_i32_e32 v0, 6, v0
	v_lshrrev_b32_e32 v4, 6, v3
	v_and_b32_e32 v3, 0xc0, v3
	v_lshlrev_b32_e32 v2, 3, v0
	v_lshlrev_b32_e32 v0, 5, v0
	v_sub_u32_e32 v1, v1, v3
	v_mov_b32_e32 v3, 1
	v_and_b32_e32 v2, 0x1ffff0, v2
	v_and_b32_e32 v0, 32, v0
	v_ashrrev_i16_sdwa v1, v3, sext(v1) dst_sel:DWORD dst_unused:UNUSED_PAD src0_sel:DWORD src1_sel:BYTE_0
	v_add_u32_sdwa v0, v0, sext(v1) dst_sel:DWORD dst_unused:UNUSED_PAD src0_sel:DWORD src1_sel:WORD_0
	v_add_lshl_u32 v1, v4, v2, 12
	v_add_u32_e32 v140, 0x2000, v138
	v_lshl_add_u32 v139, v0, 1, v1
	v_ashrrev_i32_e32 v0, 31, v140
	v_lshrrev_b32_e32 v0, 22, v0
	v_add_u32_e32 v0, v140, v0
	v_ashrrev_i32_e32 v0, 10, v0
	v_mul_i32_i24_e32 v1, 0x400, v0
	v_sub_u32_e32 v1, v140, v1
	v_lshrrev_b32_e32 v2, 4, v1
	v_bitop3_b32 v1, v2, v1, 32 bitop3:0x6c
	v_ashrrev_i32_e32 v4, 31, v1
	v_lshrrev_b32_e32 v4, 26, v4
	v_add_u32_e32 v4, v1, v4
	v_lshrrev_b32_e32 v5, 6, v4
	v_and_b32_e32 v4, 0xc0, v4
	v_lshlrev_b32_e32 v2, 3, v0
	v_lshlrev_b32_e32 v0, 5, v0
	v_sub_u32_e32 v1, v1, v4
	s_add_u32 s12, s8, 0x2242000
	v_and_b32_e32 v2, 0x1ffff0, v2
	v_and_b32_e32 v0, 32, v0
	v_ashrrev_i16_sdwa v1, v3, sext(v1) dst_sel:DWORD dst_unused:UNUSED_PAD src0_sel:DWORD src1_sel:BYTE_0
	s_addc_u32 s0, s22, 0
	v_add_u32_sdwa v0, v0, sext(v1) dst_sel:DWORD dst_unused:UNUSED_PAD src0_sel:DWORD src1_sel:WORD_0
	v_add_lshl_u32 v1, v5, v2, 12
	s_and_b32 s13, s0, 0xffff
	s_and_b32 s9, s22, 0xffff
	v_lshl_add_u32 v141, v0, 1, v1
	v_and_b32_e32 v0, 15, v195
	v_bfe_u32 v1, v252, 4, 2
	s_and_b32 s3, s2, 3
	s_ashr_i32 s4, s2, 2
	s_cmp_eq_u32 s4, 1
	v_lshlrev_b32_e32 v2, 4, v1
	v_lshlrev_b32_e32 v3, 6, v0
	v_lshlrev_b32_e32 v5, 2, v195
	s_cselect_b64 s[0:1], -1, 0
	s_lshl_b32 s5, s3, 12
	v_or_b32_e32 v4, v2, v3
	v_and_b32_e32 v5, 32, v5
	s_mov_b32 s6, 0x10000
	v_bitop3_b32 v6, v4, s6, v5 bitop3:0xde
	s_mov_b32 s6, 0x14000
	s_cmp_lt_u32 s2, 4
	v_bitop3_b32 v7, v4, s6, v5 bitop3:0xde
	s_mov_b32 s6, 0x18000
	s_cselect_b64 s[16:17], -1, 0
	s_lshl_b32 s24, s3, 5
	v_bitop3_b32 v8, v4, s6, v5 bitop3:0xde
	s_mov_b32 s6, 0x1c000
	v_lshlrev_b32_e32 v1, 2, v1
	s_lshl_b32 s2, s4, 13
	s_or_b32 s25, s24, 0x80
	v_bitop3_b32 v4, v4, s6, v5 bitop3:0xde
	v_lshl_or_b32 v142, s4, 6, v1
	s_or_b32 s4, s2, 0x800
	s_or_b32 s6, s2, 0x1000
	s_or_b32 s7, s2, 0x1800
	v_lshl_or_b32 v144, s3, 4, v0
	s_lshr_b32 s3, s25, 1
	v_lshlrev_b32_e32 v10, 6, v195
	s_add_u32 s18, s8, 0x4442000
	v_lshrrev_b32_e32 v9, 2, v252
	v_and_b32_e32 v10, 0x3c0, v10
	s_addc_u32 s19, s22, 0
	s_mov_b32 s15, 0x20000
	v_bitop3_b32 v3, v2, v5, v3 bitop3:0x36
	v_or_b32_e32 v143, s24, v0
	v_and_b32_e32 v9, 4, v9
	v_bitop3_b32 v2, v10, v5, v2 bitop3:0x36
	v_mov_b32_e32 v145, 0x800
	v_or_b32_e32 v147, s3, v0
	s_add_u32 s20, s8, 0x2040000
	v_cndmask_b32_e64 v0, 0, 1, s[0:1]
	s_mov_b32 s14, 0x2200000
	s_mov_b32 s10, 0xc00000
	s_mov_b32 s11, s15
	v_and_or_b32 v146, v1, 4, v145
	v_or_b32_e32 v148, 0x800, v9
	v_or_b32_e32 v149, 0x801, v9
	v_or_b32_e32 v150, 0x802, v9
	v_or_b32_e32 v151, 0x803, v9
	v_add_u32_e32 v152, 0x10000, v138
	v_add_u32_e32 v153, 0x12000, v138
	v_add_u32_e32 v154, 0x14000, v138
	v_add_u32_e32 v155, 0x16000, v138
	s_movk_i32 s26, 0x4000
	v_add_u32_e32 v156, 0x4000, v138
	v_add_u32_e32 v157, 0x6000, v138
	v_add_u32_e32 v158, 0x18000, v138
	v_add_u32_e32 v159, 0x1a000, v138
	v_add_u32_e32 v160, 0x8000, v138
	v_add_u32_e32 v161, 0xa000, v138
	v_add_u32_e32 v162, 0x1c000, v138
	v_add_u32_e32 v163, 0x1e000, v138
	v_add_u32_e32 v164, 0xc000, v138
	v_add_u32_e32 v165, 0xe000, v138
	s_addc_u32 s21, s22, 0
	s_movk_i32 s27, 0xcd
	v_add_u32_e32 v166, s5, v6
	v_add_u32_e32 v167, s2, v3
	v_add_u32_e32 v168, s4, v2
	v_add_u32_e32 v169, s6, v2
	v_add_u32_e32 v170, s7, v2
	v_add_u32_e32 v171, s5, v7
	v_add_u32_e32 v172, s5, v8
	v_add_u32_e32 v173, s5, v4
	s_movk_i32 s28, 0x3080
	v_mov_b32_e32 v129, 0
	s_movk_i32 s29, 0x7cd
	s_movk_i32 s30, 0x7ce
	s_movk_i32 s31, 0x7cf
	s_movk_i32 s34, 0x7dd
	s_movk_i32 s35, 0x7de
	s_movk_i32 s36, 0x7df
	s_movk_i32 s37, 0x7ed
	s_movk_i32 s38, 0x7ee
	s_movk_i32 s39, 0x7ef
	s_movk_i32 s40, 0x7fd
	s_movk_i32 s41, 0x7fe
	s_movk_i32 s42, 0x7ff
	v_cmp_ne_u32_e64 s[2:3], 1, v0
	s_mov_b32 s43, s78
	s_add_u32 s8, s84, 0x1c40000
	s_addc_u32 s0, s85, 0
	s_and_b32 s9, s0, 0xffff
	s_mov_b32 s10, 0x400000
	s_add_u32 s12, s84, 0x11262000
	s_addc_u32 s0, s85, 0
	s_and_b32 s13, s0, 0xffff
	s_mov_b32 s14, 0x4400000
	s_add_u32 s18, s84, 0x15662000
	s_addc_u32 s19, s85, 0
	s_mov_b32 s70, s78
	s_cmp_ge_u32 s70, 0x100
	s_cbranch_scc1 .Lq8_skip
;     ...
;   for (int tile0 = rev ? (int)(gridDim.x - 1 - blockIdx.x) : (int)blockIdx.x; tile0 < ntiles * rep; tile0 += gridDim.x) {
;     const int tile = tile0 % ntiles;
;     int mt = tile / NT, nt = tile - mt * NT + nt0;
;     if (EPI == 1 && NT == 8 && mtiles == 64 && gridDim.x == 256) {
;       const int blk = tile & 255, rnd = tile >> 8;
;       mt = rnd * 32 + (blk & 7) * 4 + (blk >> 6);
;       nt = (blk >> 3) & 7;
;     }
;     const int m0 = mt * BM, n0 = nt * BN;
;     const bool skip_mma = (EPI == 2) && (n0 >= 6144) && (wn == 1);
;     if (NH > 0) {
;       for (int idx = tid; idx < BM * NH; idx += NTHR) {
;         int row = idx / NH, h = idx % NH;
;         const float* pp = parts + (size_t)(m0 + row) * 64 + h * (64 / NH);
;         float s = 0.f;
; #pragma unroll
;         for (int q = 0; q < 64 / NH; ++q) s += pp[q];
;         rstdS[idx] = rsqrtf(s / (float)(K / NH) + 1e-6f);
;       }
;     }
;     u32x4 ra[2][4], rb[2][2];
;     const u16* ap = A + (size_t)(m0 + srow) * K + skc * 8;
;     const u16* bp = Bt + (size_t)(n0 + srow) * K + skc * 8;
; #pragma unroll
;     for (int i = 0; i < 4; ++i) ra[0][i] = *(const u32x4*)(ap + (size_t)(64 * i) * K);
; #pragma unroll
;     for (int i = 0; i < 2; ++i) rb[0][i] = *(const u32x4*)(bp + (size_t)(64 * i) * K);
; #pragma unroll
;     for (int i = 0; i < 4; ++i) ra[1][i] = *(const u32x4*)(ap + (size_t)(64 * i) * K + BK);
; #pragma unroll
;     for (int i = 0; i < 2; ++i) rb[1][i] = *(const u32x4*)(bp + (size_t)(64 * i) * K + BK);
;     {
;       unsigned char* base = smem;
; #pragma unroll
;       for (int i = 0; i < 4; ++i) *(u32x4*)(base + (srow + 64 * i) * LR + skc * 16) = ra[0][i];
; #pragma unroll
;       for (int i = 0; i < 2; ++i) *(u32x4*)(base + BM * LR + (srow + 64 * i) * LR + skc * 16) = rb[0][i];
;     }
;     __syncthreads();
.Lq8_tile:
	s_and_b32 s0, s70, 7
	s_lshr_b32 s1, s70, 3
	s_lshl_b32 s4, s0, 3
	s_lshr_b32 s0, s1, 2
	s_add_i32 s4, s4, s0
	s_and_b32 s1, s1, 3
	s_lshl_b32 s5, s4, 20
	s_lshl_b32 s6, s1, 20
	s_mov_b32 s7, s5
	v_writelane_b32 v255, s4, 51
	v_writelane_b32 v255, s1, 52
	v_mov_b32_e32 v200, v252
	v_lshrrev_b32_e32 v201, 3, v200
	v_and_b32_e32 v202, 7, v200
	v_lshl_add_u32 v201, s4, 8, v201
	v_lshlrev_b32_e32 v201, 8, v201
	v_lshl_add_u32 v203, v202, 5, v201
	global_load_dwordx4 v[208:211], v203, s[18:19]
	global_load_dwordx4 v[212:215], v203, s[18:19] offset:16
	v_add_u32_e32 v200, 512, v252
	v_lshrrev_b32_e32 v201, 3, v200
	v_and_b32_e32 v202, 7, v200
	v_lshl_add_u32 v201, s4, 8, v201
	v_lshlrev_b32_e32 v201, 8, v201
	v_lshl_add_u32 v204, v202, 5, v201
	global_load_dwordx4 v[216:219], v204, s[18:19]
	global_load_dwordx4 v[220:223], v204, s[18:19] offset:16
	v_add_u32_e32 v200, 1024, v252
	v_lshrrev_b32_e32 v201, 3, v200
	v_and_b32_e32 v202, 7, v200
	v_lshl_add_u32 v201, s4, 8, v201
	v_lshlrev_b32_e32 v201, 8, v201
	v_lshl_add_u32 v205, v202, 5, v201
	global_load_dwordx4 v[224:227], v205, s[18:19]
	global_load_dwordx4 v[228:231], v205, s[18:19] offset:16
	v_add_u32_e32 v200, 1536, v252
	v_lshrrev_b32_e32 v201, 3, v200
	v_and_b32_e32 v202, 7, v200
	v_lshl_add_u32 v201, s4, 8, v201
	v_lshlrev_b32_e32 v201, 8, v201
	v_lshl_add_u32 v206, v202, 5, v201
	global_load_dwordx4 v[232:235], v206, s[18:19]
	global_load_dwordx4 v[236:239], v206, s[18:19] offset:16
	v_readfirstlane_b32 s44, v152
	s_nop 1
	s_mov_b32 m0, s44
	s_nop 0
	buffer_load_dwordx4 v139, s[8:11], s6 offen lds
	v_readfirstlane_b32 s44, v153
	s_nop 1
	s_mov_b32 m0, s44
	s_nop 0
	buffer_load_dwordx4 v141, s[8:11], s6 offen lds
	v_readfirstlane_b32 s44, v138
	s_nop 1
	s_mov_b32 m0, s44
	s_nop 0
	buffer_load_dwordx4 v139, s[12:15], s5 offen lds
	v_readfirstlane_b32 s44, v140
	s_nop 1
	s_mov_b32 m0, s44
	s_nop 0
	buffer_load_dwordx4 v141, s[12:15], s5 offen lds
	s_or_b32 s45, s6, 0x80000
	v_readfirstlane_b32 s44, v154
	s_nop 1
	s_mov_b32 m0, s44
	s_nop 0
	buffer_load_dwordx4 v139, s[8:11], s45 offen lds
	v_readfirstlane_b32 s44, v155
	s_nop 1
	s_mov_b32 m0, s44
	s_nop 0
	buffer_load_dwordx4 v141, s[8:11], s45 offen lds
	s_or_b32 s45, s5, 0x80000
	v_readfirstlane_b32 s44, v156
	s_nop 1
	s_mov_b32 m0, s44
	s_nop 0
	buffer_load_dwordx4 v139, s[12:15], s45 offen lds
	v_readfirstlane_b32 s44, v157
	s_nop 1
	s_mov_b32 m0, s44
	s_nop 0
	buffer_load_dwordx4 v141, s[12:15], s45 offen lds
	s_waitcnt vmcnt(8)
	v_add_f32_e32 v200, 0, v208
	v_add_f32_e32 v200, v200, v209
	v_add_f32_e32 v200, v200, v210
	v_add_f32_e32 v200, v200, v211
	v_add_f32_e32 v200, v200, v212
	v_add_f32_e32 v200, v200, v213
	v_add_f32_e32 v200, v200, v214
	v_add_f32_e32 v200, v200, v215
	v_mov_b32_e32 v201, 0x358637bd
	v_fmac_f32_e32 v201, 0x3b800000, v200
	v_rsq_f32_e32 v201, v201
	v_lshlrev_b32_e32 v202, 2, v252
	v_add_u32_e32 v202, 0x20000, v202
	ds_write_b32 v202, v201
	v_add_f32_e32 v200, 0, v216
	v_add_f32_e32 v200, v200, v217
	v_add_f32_e32 v200, v200, v218
	v_add_f32_e32 v200, v200, v219
	v_add_f32_e32 v200, v200, v220
	v_add_f32_e32 v200, v200, v221
	v_add_f32_e32 v200, v200, v222
	v_add_f32_e32 v200, v200, v223
	v_mov_b32_e32 v201, 0x358637bd
	v_fmac_f32_e32 v201, 0x3b800000, v200
	v_rsq_f32_e32 v201, v201
	v_lshlrev_b32_e32 v202, 2, v252
	v_add_u32_e32 v202, 0x20800, v202
	ds_write_b32 v202, v201
	v_add_f32_e32 v200, 0, v224
	v_add_f32_e32 v200, v200, v225
	v_add_f32_e32 v200, v200, v226
	v_add_f32_e32 v200, v200, v227
	v_add_f32_e32 v200, v200, v228
	v_add_f32_e32 v200, v200, v229
	v_add_f32_e32 v200, v200, v230
	v_add_f32_e32 v200, v200, v231
	v_mov_b32_e32 v201, 0x358637bd
	v_fmac_f32_e32 v201, 0x3b800000, v200
	v_rsq_f32_e32 v201, v201
	v_lshlrev_b32_e32 v202, 2, v252
	v_add_u32_e32 v202, 0x21000, v202
	ds_write_b32 v202, v201
	v_add_f32_e32 v200, 0, v232
	v_add_f32_e32 v200, v200, v233
	v_add_f32_e32 v200, v200, v234
	v_add_f32_e32 v200, v200, v235
	v_add_f32_e32 v200, v200, v236
	v_add_f32_e32 v200, v200, v237
	v_add_f32_e32 v200, v200, v238
	v_add_f32_e32 v200, v200, v239
	v_mov_b32_e32 v201, 0x358637bd
	v_fmac_f32_e32 v201, 0x3b800000, v200
	v_rsq_f32_e32 v201, v201
	v_lshlrev_b32_e32 v202, 2, v252
	v_add_u32_e32 v202, 0x21800, v202
	ds_write_b32 v202, v201
	v_and_b32_e32 v128, 15, v195
	v_lshrrev_b32_e32 v129, 2, v252
	v_and_b32_e32 v129, 64, v129
	v_add_u32_e32 v128, v128, v129
	v_lshlrev_b32_e32 v128, 5, v128
	v_add_u32_e32 v128, 0x20000, v128
	s_waitcnt lgkmcnt(0)
	s_and_b64 vcc, exec, s[2:3]
	s_cbranch_vccnz .Lq8_201
	s_barrier

;     ...
;       if (NH > 0) {
;         const int per = KT / NH;
;         if (((kt + 1) % per) == 0) {
;           const int h = (kt + 1) / per - 1;
; #pragma unroll
;           for (int mf = 0; mf < 4; ++mf)
; #pragma unroll
;             for (int r = 0; r < 4; ++r) {
;               float s = rstdS[(wm * 64 + mf * 16 + 4 * g + r) * NH + h];
; #pragma unroll
;               for (int nf = 0; nf < 4; ++nf) {
;                 accT[mf][nf][r] += s * acc[mf][nf][r];
;                 acc[mf][nf][r] = 0.f;
;               }
;             }
;         }
;       }
;       if (kt + 1 < KT) {
;         unsigned char* base = smem + (par ^ 1) * BUFB;
; #pragma unroll
;         for (int i = 0; i < 4; ++i) *(u32x4*)(base + (srow + 64 * i) * LR + skc * 16) = ra[par ^ 1][i];
; #pragma unroll
;         for (int i = 0; i < 2; ++i) *(u32x4*)(base + BM * LR + (srow + 64 * i) * LR + skc * 16) = rb[par ^ 1][i];
;       }
;       __syncthreads();
;      }
;     }
; #pragma unroll
;     for (int mf = 0; mf < 4; ++mf) {
;       __builtin_amdgcn_sched_barrier(0);
;       float rvv[4][4];
;       if (EPI == 1) {
; #pragma unroll
;         for (int r = 0; r < 4; ++r) {
;           const int row = m0 + wm * 64 + mf * 16 + 4 * g + r;
; #pragma unroll
;           for (int nf = 0; nf < 4; ++nf) {
;             const int col = n0 + wn * 64 + nf * 16 + l15;
;             rvv[r][nf] = resid ? resid[(size_t)row * 1024 + col] : xrow(p, row)[col];
;           }
;         }
;       }
.Lq8_205:
	v_add_u32_e32 v220, 28, v128
	ds_read_b32 v221, v220
	ds_read_b32 v223, v220 offset:512
	ds_read_b32 v225, v220 offset:1024
	ds_read_b32 v227, v220 offset:1536
	ds_read_b32 v229, v220 offset:4096
	ds_read_b32 v231, v220 offset:4608
	ds_read_b32 v233, v220 offset:5120
	ds_read_b32 v235, v220 offset:5632
	s_waitcnt lgkmcnt(0)
	s_nop 7
	v_mul_f32_e32 v120, v221, v120
	v_mul_f32_e32 v121, v221, v121
	v_mul_f32_e32 v122, v221, v122
	v_mul_f32_e32 v123, v221, v123
	v_mul_f32_e32 v124, v221, v124
	v_mul_f32_e32 v125, v221, v125
	v_mul_f32_e32 v126, v221, v126
	v_mul_f32_e32 v127, v221, v127
	v_mul_f32_e32 v112, v221, v112
	v_mul_f32_e32 v113, v221, v113
	v_mul_f32_e32 v114, v221, v114
	v_mul_f32_e32 v115, v221, v115
	v_mul_f32_e32 v116, v221, v116
	v_mul_f32_e32 v117, v221, v117
	v_mul_f32_e32 v118, v221, v118
	v_mul_f32_e32 v119, v221, v119
	v_mul_f32_e32 v104, v223, v104
	v_mul_f32_e32 v105, v223, v105
	v_mul_f32_e32 v106, v223, v106
	v_mul_f32_e32 v107, v223, v107
	v_mul_f32_e32 v108, v223, v108
	v_mul_f32_e32 v109, v223, v109
	v_mul_f32_e32 v110, v223, v110
	v_mul_f32_e32 v111, v223, v111
	v_mul_f32_e32 v96, v223, v96
	v_mul_f32_e32 v97, v223, v97
	v_mul_f32_e32 v98, v223, v98
	v_mul_f32_e32 v99, v223, v99
	v_mul_f32_e32 v100, v223, v100
	v_mul_f32_e32 v101, v223, v101
	v_mul_f32_e32 v102, v223, v102
	v_mul_f32_e32 v103, v223, v103
	v_mul_f32_e32 v88, v225, v88
	v_mul_f32_e32 v89, v225, v89
	v_mul_f32_e32 v90, v225, v90
	v_mul_f32_e32 v91, v225, v91
	v_mul_f32_e32 v92, v225, v92
	v_mul_f32_e32 v93, v225, v93
	v_mul_f32_e32 v94, v225, v94
	v_mul_f32_e32 v95, v225, v95
	v_mul_f32_e32 v80, v225, v80
	v_mul_f32_e32 v81, v225, v81
	v_mul_f32_e32 v82, v225, v82
	v_mul_f32_e32 v83, v225, v83
	v_mul_f32_e32 v84, v225, v84
	v_mul_f32_e32 v85, v225, v85
	v_mul_f32_e32 v86, v225, v86
	v_mul_f32_e32 v87, v225, v87
	v_mul_f32_e32 v72, v227, v72
	v_mul_f32_e32 v73, v227, v73
	v_mul_f32_e32 v74, v227, v74
	v_mul_f32_e32 v75, v227, v75
	v_mul_f32_e32 v76, v227, v76
	v_mul_f32_e32 v77, v227, v77
	v_mul_f32_e32 v78, v227, v78
	v_mul_f32_e32 v79, v227, v79
	v_mul_f32_e32 v64, v227, v64
	v_mul_f32_e32 v65, v227, v65
	v_mul_f32_e32 v66, v227, v66
	v_mul_f32_e32 v67, v227, v67
	v_mul_f32_e32 v68, v227, v68
	v_mul_f32_e32 v69, v227, v69
	v_mul_f32_e32 v70, v227, v70
	v_mul_f32_e32 v71, v227, v71
	v_mul_f32_e32 v56, v229, v56
	v_mul_f32_e32 v57, v229, v57
	v_mul_f32_e32 v58, v229, v58
	v_mul_f32_e32 v59, v229, v59
	v_mul_f32_e32 v60, v229, v60
	v_mul_f32_e32 v61, v229, v61
	v_mul_f32_e32 v62, v229, v62
	v_mul_f32_e32 v63, v229, v63
	v_mul_f32_e32 v48, v229, v48
	v_mul_f32_e32 v49, v229, v49
	v_mul_f32_e32 v50, v229, v50
	v_mul_f32_e32 v51, v229, v51
	v_mul_f32_e32 v52, v229, v52
	v_mul_f32_e32 v53, v229, v53
	v_mul_f32_e32 v54, v229, v54
	v_mul_f32_e32 v55, v229, v55
	v_mul_f32_e32 v40, v231, v40
	v_mul_f32_e32 v41, v231, v41
	v_mul_f32_e32 v42, v231, v42
	v_mul_f32_e32 v43, v231, v43
	v_mul_f32_e32 v44, v231, v44
	v_mul_f32_e32 v45, v231, v45
	v_mul_f32_e32 v46, v231, v46
	v_mul_f32_e32 v47, v231, v47
	v_mul_f32_e32 v32, v231, v32
	v_mul_f32_e32 v33, v231, v33
	v_mul_f32_e32 v34, v231, v34
	v_mul_f32_e32 v35, v231, v35
	v_mul_f32_e32 v36, v231, v36
	v_mul_f32_e32 v37, v231, v37
	v_mul_f32_e32 v38, v231, v38
	v_mul_f32_e32 v39, v231, v39
	v_mul_f32_e32 v24, v233, v24
	v_mul_f32_e32 v25, v233, v25
	v_mul_f32_e32 v26, v233, v26
	v_mul_f32_e32 v27, v233, v27
	v_mul_f32_e32 v28, v233, v28
	v_mul_f32_e32 v29, v233, v29
	v_mul_f32_e32 v30, v233, v30
	v_mul_f32_e32 v31, v233, v31
	v_mul_f32_e32 v16, v233, v16
	v_mul_f32_e32 v17, v233, v17
	v_mul_f32_e32 v18, v233, v18
	v_mul_f32_e32 v19, v233, v19
	v_mul_f32_e32 v20, v233, v20
	v_mul_f32_e32 v21, v233, v21
	v_mul_f32_e32 v22, v233, v22
	v_mul_f32_e32 v23, v233, v23
	v_mul_f32_e32 v8, v235, v8
	v_mul_f32_e32 v9, v235, v9
	v_mul_f32_e32 v10, v235, v10
	v_mul_f32_e32 v11, v235, v11
	v_mul_f32_e32 v12, v235, v12
	v_mul_f32_e32 v13, v235, v13
	v_mul_f32_e32 v14, v235, v14
	v_mul_f32_e32 v15, v235, v15
	v_mul_f32_e32 v0, v235, v0
	v_mul_f32_e32 v1, v235, v1
	v_mul_f32_e32 v2, v235, v2
	v_mul_f32_e32 v3, v235, v3
	v_mul_f32_e32 v4, v235, v4
	v_mul_f32_e32 v5, v235, v5
	v_mul_f32_e32 v6, v235, v6
	v_mul_f32_e32 v7, v235, v7
	s_barrier
	v_readlane_b32 s4, v255, 51
	v_readlane_b32 s1, v255, 52
	v_readlane_b32 s5, v255, 6
	v_and_b32_e32 v176, 15, v195
	v_lshrrev_b32_e32 v177, 4, v195
	s_lshr_b32 s6, s5, 2
	s_and_b32 s7, s5, 3
	s_lshl_b32 s6, s6, 6
	v_add_u32_e32 v178, s6, v176
	v_mul_u32_u24_e32 v178, 0x410, v178
	s_lshl_b32 s7, s7, 7
	v_lshl_add_u32 v178, v177, 4, v178
	v_add_u32_e32 v178, s7, v178
	s_lshl_b32 s7, s5, 4
	v_lshlrev_b32_e32 v179, 4, v195
	s_mul_i32 s6, s7, 0x410
	v_add_u32_e32 v180, s6, v179
	s_lshl_b32 s4, s4, 8
	s_add_i32 s4, s4, s7
	s_lshl_b32 s4, s4, 12
	s_lshl_b32 s1, s1, 10
	s_add_i32 s4, s4, s1
	v_add_u32_e32 v181, s4, v179
	s_add_u32 s20, s84, 0x15aa2000
	s_addc_u32 s21, s85, 0
	s_add_u32 s24, s84, 0x19ea2000
	s_addc_u32 s25, s85, 0
	v_mov_b32_e32 v182, v181
	global_load_dwordx4 v[184:187], v182, s[20:21]
	v_add_u32_e32 v182, 0x1000, v182
	global_load_dwordx4 v[188:191], v182, s[20:21]
	v_add_u32_e32 v182, 0x1000, v182
	global_load_dwordx4 v[196:199], v182, s[20:21]
	v_add_u32_e32 v182, 0x1000, v182
	global_load_dwordx4 v[200:203], v182, s[20:21]
	v_add_u32_e32 v182, 0x1000, v182
	global_load_dwordx4 v[204:207], v182, s[20:21]
	v_add_u32_e32 v182, 0x1000, v182
	global_load_dwordx4 v[208:211], v182, s[20:21]
	v_add_u32_e32 v182, 0x1000, v182
	global_load_dwordx4 v[212:215], v182, s[20:21]
	v_add_u32_e32 v182, 0x1000, v182
	global_load_dwordx4 v[216:219], v182, s[20:21]
	v_add_u32_e32 v182, 0x1000, v182
	global_load_dwordx4 v[220:223], v182, s[20:21]
	v_add_u32_e32 v182, 0x1000, v182
	global_load_dwordx4 v[224:227], v182, s[20:21]
	v_add_u32_e32 v182, 0x1000, v182
	global_load_dwordx4 v[228:231], v182, s[20:21]
	v_add_u32_e32 v182, 0x1000, v182
	global_load_dwordx4 v[232:235], v182, s[20:21]
	v_add_u32_e32 v182, 0x1000, v182
	global_load_dwordx4 v[236:239], v182, s[20:21]
	v_add_u32_e32 v182, 0x1000, v182
	global_load_dwordx4 v[240:243], v182, s[20:21]
	v_add_u32_e32 v182, 0x1000, v182
	global_load_dwordx4 v[244:247], v182, s[20:21]
	v_add_u32_e32 v182, 0x1000, v182
	global_load_dwordx4 v[248:251], v182, s[20:21]
	ds_write_b128 v178, v[120:123]
	ds_write_b128 v178, v[124:127] offset:64
	ds_write_b128 v178, v[104:107] offset:16640
	ds_write_b128 v178, v[108:111] offset:16704
	ds_write_b128 v178, v[88:91] offset:33280
	ds_write_b128 v178, v[92:95] offset:33344
	ds_write_b128 v178, v[72:75] offset:49920
	ds_write_b128 v178, v[76:79] offset:49984
	ds_write_b128 v178, v[112:115] offset:512
	ds_write_b128 v178, v[116:119] offset:576
	ds_write_b128 v178, v[96:99] offset:17152
	ds_write_b128 v178, v[100:103] offset:17216
	ds_write_b128 v178, v[80:83] offset:33792
	ds_write_b128 v178, v[84:87] offset:33856
	ds_write_b128 v178, v[64:67] offset:50432
	ds_write_b128 v178, v[68:71] offset:50496
	s_waitcnt lgkmcnt(0)
	s_barrier
;     ...
; #pragma unroll
;     for (int mf = 0; mf < 4; ++mf) {
;       __builtin_amdgcn_sched_barrier(0);
;       float rvv[4][4];
;       if (EPI == 1) {
; #pragma unroll
;         for (int r = 0; r < 4; ++r) {
;           const int row = m0 + wm * 64 + mf * 16 + 4 * g + r;
; #pragma unroll
;           for (int nf = 0; nf < 4; ++nf) {
;             const int col = n0 + wn * 64 + nf * 16 + l15;
;             rvv[r][nf] = resid ? resid[(size_t)row * 1024 + col] : xrow(p, row)[col];
;           }
;         }
;       }
; #pragma unroll
;       for (int r = 0; r < 4; ++r) {
;         const int row = m0 + wm * 64 + mf * 16 + 4 * g + r;
;         if (EPI == 0) {
;           u16* proj = (u16*)(p.ws + OFF_PROJ) + (size_t)row * PROJ_LD;
;           if (n0 < 2048) {
;             const float2* rope = (const float2*)(p.ws + OFF_ROPE);
;             const int pi = row < NPROMPT ? (row & 2047) : 2048 + ((row - NPROMPT) & 7);
; #pragma unroll
;             for (int np = 0; np < 2; ++np) {
;               const int pc = n0 + wn * 64 + np * 32;
;               const int i = ((pc & 255) >> 5) * 16 + l15;
;               const float2 cs = rope[pi * 128 + i];
;               const float x1 = acc[mf][2 * np][r], x2 = acc[mf][2 * np + 1][r];
;               float y1 = x1 * cs.x - x2 * cs.y, y2 = x1 * cs.y + x2 * cs.x;
;               if (pc >= 1024) { y1 *= 0.0625f; y2 *= 0.0625f; }
;               const int f1 = (pc & ~255) + i;
;               proj[f1] = f2bf(y1);
;               proj[f1 + 128] = f2bf(y2);
;             }
;           } else {
; #pragma unroll
;             for (int nf = 0; nf < 4; ++nf) proj[n0 + wn * 64 + nf * 16 + l15] = f2bf(acc[mf][nf][r]);
;           }
;         } else if (EPI == 1) {
; #pragma unroll
;           for (int nf = 0; nf < 4; ++nf) {
;             const int col = n0 + wn * 64 + nf * 16 + l15;
;             const float a = (NH > 0) ? accT[mf][nf][r] : acc[mf][nf][r];
;             outf[(size_t)row * 1024 + col] = rvv[r][nf] + a;
;           }
	ds_read_b128 v[64:67], v180
	ds_read_b128 v[68:71], v180 offset:1040
	ds_read_b128 v[72:75], v180 offset:2080
	ds_read_b128 v[76:79], v180 offset:3120
	ds_read_b128 v[80:83], v180 offset:4160
	ds_read_b128 v[84:87], v180 offset:5200
	ds_read_b128 v[88:91], v180 offset:6240
	ds_read_b128 v[92:95], v180 offset:7280
	ds_read_b128 v[96:99], v180 offset:8320
	ds_read_b128 v[100:103], v180 offset:9360
	ds_read_b128 v[104:107], v180 offset:10400
	ds_read_b128 v[108:111], v180 offset:11440
	ds_read_b128 v[112:115], v180 offset:12480
	ds_read_b128 v[116:119], v180 offset:13520
	ds_read_b128 v[120:123], v180 offset:14560
	ds_read_b128 v[124:127], v180 offset:15600
	s_waitcnt lgkmcnt(0)
	s_barrier
	v_mov_b32_e32 v182, v181
	s_waitcnt vmcnt(15)
	v_add_f32_e32 v64, v64, v184
	v_add_f32_e32 v65, v65, v185
	v_add_f32_e32 v66, v66, v186
	v_add_f32_e32 v67, v67, v187
	global_store_dwordx4 v182, v[64:67], s[24:25]
	v_add_u32_e32 v182, 0x1000, v182
	s_waitcnt vmcnt(15)
	v_add_f32_e32 v68, v68, v188
	v_add_f32_e32 v69, v69, v189
	v_add_f32_e32 v70, v70, v190
	v_add_f32_e32 v71, v71, v191
	global_store_dwordx4 v182, v[68:71], s[24:25]
	v_add_u32_e32 v182, 0x1000, v182
	s_waitcnt vmcnt(15)
	v_add_f32_e32 v72, v72, v196
	v_add_f32_e32 v73, v73, v197
	v_add_f32_e32 v74, v74, v198
	v_add_f32_e32 v75, v75, v199
	global_store_dwordx4 v182, v[72:75], s[24:25]
	v_add_u32_e32 v182, 0x1000, v182
	s_waitcnt vmcnt(15)
	v_add_f32_e32 v76, v76, v200
	v_add_f32_e32 v77, v77, v201
	v_add_f32_e32 v78, v78, v202
	v_add_f32_e32 v79, v79, v203
	global_store_dwordx4 v182, v[76:79], s[24:25]
	v_add_u32_e32 v182, 0x1000, v182
	s_waitcnt vmcnt(15)
	v_add_f32_e32 v80, v80, v204
	v_add_f32_e32 v81, v81, v205
	v_add_f32_e32 v82, v82, v206
	v_add_f32_e32 v83, v83, v207
	global_store_dwordx4 v182, v[80:83], s[24:25]
	v_add_u32_e32 v182, 0x1000, v182
	s_waitcnt vmcnt(15)
	v_add_f32_e32 v84, v84, v208
	v_add_f32_e32 v85, v85, v209
	v_add_f32_e32 v86, v86, v210
	v_add_f32_e32 v87, v87, v211
	global_store_dwordx4 v182, v[84:87], s[24:25]
	v_add_u32_e32 v182, 0x1000, v182
	s_waitcnt vmcnt(15)
	v_add_f32_e32 v88, v88, v212
	v_add_f32_e32 v89, v89, v213
	v_add_f32_e32 v90, v90, v214
	v_add_f32_e32 v91, v91, v215
	global_store_dwordx4 v182, v[88:91], s[24:25]
	v_add_u32_e32 v182, 0x1000, v182
	s_waitcnt vmcnt(15)
	v_add_f32_e32 v92, v92, v216
	v_add_f32_e32 v93, v93, v217
	v_add_f32_e32 v94, v94, v218
	v_add_f32_e32 v95, v95, v219
	global_store_dwordx4 v182, v[92:95], s[24:25]
	v_add_u32_e32 v182, 0x1000, v182
	s_waitcnt vmcnt(15)
	v_add_f32_e32 v96, v96, v220
	v_add_f32_e32 v97, v97, v221
	v_add_f32_e32 v98, v98, v222
	v_add_f32_e32 v99, v99, v223
	global_store_dwordx4 v182, v[96:99], s[24:25]
	v_add_u32_e32 v182, 0x1000, v182
	s_waitcnt vmcnt(15)
	v_add_f32_e32 v100, v100, v224
	v_add_f32_e32 v101, v101, v225
	v_add_f32_e32 v102, v102, v226
	v_add_f32_e32 v103, v103, v227
	global_store_dwordx4 v182, v[100:103], s[24:25]
	v_add_u32_e32 v182, 0x1000, v182
	s_waitcnt vmcnt(15)
	v_add_f32_e32 v104, v104, v228
	v_add_f32_e32 v105, v105, v229
	v_add_f32_e32 v106, v106, v230
	v_add_f32_e32 v107, v107, v231
	global_store_dwordx4 v182, v[104:107], s[24:25]
	v_add_u32_e32 v182, 0x1000, v182
	s_waitcnt vmcnt(15)
	v_add_f32_e32 v108, v108, v232
	v_add_f32_e32 v109, v109, v233
	v_add_f32_e32 v110, v110, v234
	v_add_f32_e32 v111, v111, v235
	global_store_dwordx4 v182, v[108:111], s[24:25]
	v_add_u32_e32 v182, 0x1000, v182
	s_waitcnt vmcnt(15)
	v_add_f32_e32 v112, v112, v236
	v_add_f32_e32 v113, v113, v237
	v_add_f32_e32 v114, v114, v238
	v_add_f32_e32 v115, v115, v239
	global_store_dwordx4 v182, v[112:115], s[24:25]
	v_add_u32_e32 v182, 0x1000, v182
	s_waitcnt vmcnt(15)
	v_add_f32_e32 v116, v116, v240
	v_add_f32_e32 v117, v117, v241
	v_add_f32_e32 v118, v118, v242
	v_add_f32_e32 v119, v119, v243
	global_store_dwordx4 v182, v[116:119], s[24:25]
	v_add_u32_e32 v182, 0x1000, v182
	s_waitcnt vmcnt(15)
	v_add_f32_e32 v120, v120, v244
	v_add_f32_e32 v121, v121, v245
	v_add_f32_e32 v122, v122, v246
	v_add_f32_e32 v123, v123, v247
	global_store_dwordx4 v182, v[120:123], s[24:25]
	v_add_u32_e32 v182, 0x1000, v182
	s_waitcnt vmcnt(15)
	v_add_f32_e32 v124, v124, v248
	v_add_f32_e32 v125, v125, v249
	v_add_f32_e32 v126, v126, v250
	v_add_f32_e32 v127, v127, v251
	global_store_dwordx4 v182, v[124:127], s[24:25]
	v_add_u32_e32 v181, 0x80000, v181
	v_mov_b32_e32 v182, v181
	global_load_dwordx4 v[184:187], v182, s[20:21]
	v_add_u32_e32 v182, 0x1000, v182
	global_load_dwordx4 v[188:191], v182, s[20:21]
	v_add_u32_e32 v182, 0x1000, v182
	global_load_dwordx4 v[196:199], v182, s[20:21]
	v_add_u32_e32 v182, 0x1000, v182
	global_load_dwordx4 v[200:203], v182, s[20:21]
	v_add_u32_e32 v182, 0x1000, v182
	global_load_dwordx4 v[204:207], v182, s[20:21]
	v_add_u32_e32 v182, 0x1000, v182
	global_load_dwordx4 v[208:211], v182, s[20:21]
	v_add_u32_e32 v182, 0x1000, v182
	global_load_dwordx4 v[212:215], v182, s[20:21]
	v_add_u32_e32 v182, 0x1000, v182
	global_load_dwordx4 v[216:219], v182, s[20:21]
	v_add_u32_e32 v182, 0x1000, v182
	global_load_dwordx4 v[220:223], v182, s[20:21]
	v_add_u32_e32 v182, 0x1000, v182
	global_load_dwordx4 v[224:227], v182, s[20:21]
	v_add_u32_e32 v182, 0x1000, v182
	global_load_dwordx4 v[228:231], v182, s[20:21]
	v_add_u32_e32 v182, 0x1000, v182
	global_load_dwordx4 v[232:235], v182, s[20:21]
	v_add_u32_e32 v182, 0x1000, v182
	global_load_dwordx4 v[236:239], v182, s[20:21]
	v_add_u32_e32 v182, 0x1000, v182
	global_load_dwordx4 v[240:243], v182, s[20:21]
	v_add_u32_e32 v182, 0x1000, v182
	global_load_dwordx4 v[244:247], v182, s[20:21]
	v_add_u32_e32 v182, 0x1000, v182
	global_load_dwordx4 v[248:251], v182, s[20:21]
	ds_write_b128 v178, v[56:59]
	ds_write_b128 v178, v[60:63] offset:64
	ds_write_b128 v178, v[40:43] offset:16640
	ds_write_b128 v178, v[44:47] offset:16704
	ds_write_b128 v178, v[24:27] offset:33280
	ds_write_b128 v178, v[28:31] offset:33344
	ds_write_b128 v178, v[8:11] offset:49920
	ds_write_b128 v178, v[12:15] offset:49984
	ds_write_b128 v178, v[48:51] offset:512
	ds_write_b128 v178, v[52:55] offset:576
	ds_write_b128 v178, v[32:35] offset:17152
	ds_write_b128 v178, v[36:39] offset:17216
	ds_write_b128 v178, v[16:19] offset:33792
	ds_write_b128 v178, v[20:23] offset:33856
	ds_write_b128 v178, v[0:3] offset:50432
	ds_write_b128 v178, v[4:7] offset:50496
	s_waitcnt lgkmcnt(0)
	s_barrier
;     ...
; #pragma unroll
;     for (int mf = 0; mf < 4; ++mf) {
;       __builtin_amdgcn_sched_barrier(0);
;       float rvv[4][4];
;       if (EPI == 1) {
; #pragma unroll
;         for (int r = 0; r < 4; ++r) {
;           const int row = m0 + wm * 64 + mf * 16 + 4 * g + r;
; #pragma unroll
;           for (int nf = 0; nf < 4; ++nf) {
;             const int col = n0 + wn * 64 + nf * 16 + l15;
;             rvv[r][nf] = resid ? resid[(size_t)row * 1024 + col] : xrow(p, row)[col];
;           }
;         }
;       }
; #pragma unroll
;       for (int r = 0; r < 4; ++r) {
;         const int row = m0 + wm * 64 + mf * 16 + 4 * g + r;
;         if (EPI == 0) {
;           u16* proj = (u16*)(p.ws + OFF_PROJ) + (size_t)row * PROJ_LD;
;           if (n0 < 2048) {
;             const float2* rope = (const float2*)(p.ws + OFF_ROPE);
;             const int pi = row < NPROMPT ? (row & 2047) : 2048 + ((row - NPROMPT) & 7);
; #pragma unroll
;             for (int np = 0; np < 2; ++np) {
;               const int pc = n0 + wn * 64 + np * 32;
;               const int i = ((pc & 255) >> 5) * 16 + l15;
;               const float2 cs = rope[pi * 128 + i];
;               const float x1 = acc[mf][2 * np][r], x2 = acc[mf][2 * np + 1][r];
;               float y1 = x1 * cs.x - x2 * cs.y, y2 = x1 * cs.y + x2 * cs.x;
;               if (pc >= 1024) { y1 *= 0.0625f; y2 *= 0.0625f; }
;               const int f1 = (pc & ~255) + i;
;               proj[f1] = f2bf(y1);
;               proj[f1 + 128] = f2bf(y2);
;             }
;           } else {
; #pragma unroll
;             for (int nf = 0; nf < 4; ++nf) proj[n0 + wn * 64 + nf * 16 + l15] = f2bf(acc[mf][nf][r]);
;           }
;         } else if (EPI == 1) {
; #pragma unroll
;           for (int nf = 0; nf < 4; ++nf) {
;             const int col = n0 + wn * 64 + nf * 16 + l15;
;             const float a = (NH > 0) ? accT[mf][nf][r] : acc[mf][nf][r];
;             outf[(size_t)row * 1024 + col] = rvv[r][nf] + a;
;           }
	ds_read_b128 v[64:67], v180
	ds_read_b128 v[68:71], v180 offset:1040
	ds_read_b128 v[72:75], v180 offset:2080
	ds_read_b128 v[76:79], v180 offset:3120
	ds_read_b128 v[80:83], v180 offset:4160
	ds_read_b128 v[84:87], v180 offset:5200
	ds_read_b128 v[88:91], v180 offset:6240
	ds_read_b128 v[92:95], v180 offset:7280
	ds_read_b128 v[96:99], v180 offset:8320
	ds_read_b128 v[100:103], v180 offset:9360
	ds_read_b128 v[104:107], v180 offset:10400
	ds_read_b128 v[108:111], v180 offset:11440
	ds_read_b128 v[112:115], v180 offset:12480
	ds_read_b128 v[116:119], v180 offset:13520
	ds_read_b128 v[120:123], v180 offset:14560
	ds_read_b128 v[124:127], v180 offset:15600
	s_waitcnt lgkmcnt(0)
	s_barrier
	v_mov_b32_e32 v182, v181
	s_waitcnt vmcnt(15)
	v_add_f32_e32 v64, v64, v184
	v_add_f32_e32 v65, v65, v185
	v_add_f32_e32 v66, v66, v186
	v_add_f32_e32 v67, v67, v187
	global_store_dwordx4 v182, v[64:67], s[24:25]
	v_add_u32_e32 v182, 0x1000, v182
	s_waitcnt vmcnt(15)
	v_add_f32_e32 v68, v68, v188
	v_add_f32_e32 v69, v69, v189
	v_add_f32_e32 v70, v70, v190
	v_add_f32_e32 v71, v71, v191
	global_store_dwordx4 v182, v[68:71], s[24:25]
	v_add_u32_e32 v182, 0x1000, v182
	s_waitcnt vmcnt(15)
	v_add_f32_e32 v72, v72, v196
	v_add_f32_e32 v73, v73, v197
	v_add_f32_e32 v74, v74, v198
	v_add_f32_e32 v75, v75, v199
	global_store_dwordx4 v182, v[72:75], s[24:25]
	v_add_u32_e32 v182, 0x1000, v182
	s_waitcnt vmcnt(15)
	v_add_f32_e32 v76, v76, v200
	v_add_f32_e32 v77, v77, v201
	v_add_f32_e32 v78, v78, v202
	v_add_f32_e32 v79, v79, v203
	global_store_dwordx4 v182, v[76:79], s[24:25]
	v_add_u32_e32 v182, 0x1000, v182
	s_waitcnt vmcnt(15)
	v_add_f32_e32 v80, v80, v204
	v_add_f32_e32 v81, v81, v205
	v_add_f32_e32 v82, v82, v206
	v_add_f32_e32 v83, v83, v207
	global_store_dwordx4 v182, v[80:83], s[24:25]
	v_add_u32_e32 v182, 0x1000, v182
	s_waitcnt vmcnt(15)
	v_add_f32_e32 v84, v84, v208
	v_add_f32_e32 v85, v85, v209
	v_add_f32_e32 v86, v86, v210
	v_add_f32_e32 v87, v87, v211
	global_store_dwordx4 v182, v[84:87], s[24:25]
	v_add_u32_e32 v182, 0x1000, v182
	s_waitcnt vmcnt(15)
	v_add_f32_e32 v88, v88, v212
	v_add_f32_e32 v89, v89, v213
	v_add_f32_e32 v90, v90, v214
	v_add_f32_e32 v91, v91, v215
	global_store_dwordx4 v182, v[88:91], s[24:25]
	v_add_u32_e32 v182, 0x1000, v182
	s_waitcnt vmcnt(15)
	v_add_f32_e32 v92, v92, v216
	v_add_f32_e32 v93, v93, v217
	v_add_f32_e32 v94, v94, v218
	v_add_f32_e32 v95, v95, v219
	global_store_dwordx4 v182, v[92:95], s[24:25]
	v_add_u32_e32 v182, 0x1000, v182
	s_waitcnt vmcnt(15)
	v_add_f32_e32 v96, v96, v220
	v_add_f32_e32 v97, v97, v221
	v_add_f32_e32 v98, v98, v222
	v_add_f32_e32 v99, v99, v223
	global_store_dwordx4 v182, v[96:99], s[24:25]
	v_add_u32_e32 v182, 0x1000, v182
	s_waitcnt vmcnt(15)
	v_add_f32_e32 v100, v100, v224
	v_add_f32_e32 v101, v101, v225
	v_add_f32_e32 v102, v102, v226
	v_add_f32_e32 v103, v103, v227
	global_store_dwordx4 v182, v[100:103], s[24:25]
	v_add_u32_e32 v182, 0x1000, v182
	s_waitcnt vmcnt(15)
	v_add_f32_e32 v104, v104, v228
	v_add_f32_e32 v105, v105, v229
	v_add_f32_e32 v106, v106, v230
	v_add_f32_e32 v107, v107, v231
	global_store_dwordx4 v182, v[104:107], s[24:25]
	v_add_u32_e32 v182, 0x1000, v182
	s_waitcnt vmcnt(15)
	v_add_f32_e32 v108, v108, v232
	v_add_f32_e32 v109, v109, v233
	v_add_f32_e32 v110, v110, v234
	v_add_f32_e32 v111, v111, v235
	global_store_dwordx4 v182, v[108:111], s[24:25]
	v_add_u32_e32 v182, 0x1000, v182
	s_waitcnt vmcnt(15)
	v_add_f32_e32 v112, v112, v236
	v_add_f32_e32 v113, v113, v237
	v_add_f32_e32 v114, v114, v238
	v_add_f32_e32 v115, v115, v239
	global_store_dwordx4 v182, v[112:115], s[24:25]
	v_add_u32_e32 v182, 0x1000, v182
	s_waitcnt vmcnt(15)
	v_add_f32_e32 v116, v116, v240
	v_add_f32_e32 v117, v117, v241
	v_add_f32_e32 v118, v118, v242
	v_add_f32_e32 v119, v119, v243
	global_store_dwordx4 v182, v[116:119], s[24:25]
	v_add_u32_e32 v182, 0x1000, v182
	s_waitcnt vmcnt(15)
	v_add_f32_e32 v120, v120, v244
	v_add_f32_e32 v121, v121, v245
	v_add_f32_e32 v122, v122, v246
	v_add_f32_e32 v123, v123, v247
	global_store_dwordx4 v182, v[120:123], s[24:25]
	v_add_u32_e32 v182, 0x1000, v182
	s_waitcnt vmcnt(15)
	v_add_f32_e32 v124, v124, v248
	v_add_f32_e32 v125, v125, v249
	v_add_f32_e32 v126, v126, v250
	v_add_f32_e32 v127, v127, v251
	global_store_dwordx4 v182, v[124:127], s[24:25]
	s_waitcnt vmcnt(0)
	s_barrier
	s_add_i32 s70, s70, s96
	s_cmp_lt_u32 s70, 0x100
	s_cbranch_scc1 .Lq8_tile
.Lq8_skip:
	s_mov_b64 s[0:1], 0
	s_add_u32 s12, s84, s0
	s_addc_u32 s13, s85, s1
	v_readlane_b32 s21, v255, 6
	s_bfe_u32 s22, s90, 0x10008
	s_lshl_b32 s20, s21, 6
	s_add_i32 s22, s22, 1
	s_add_u32 s6, s12, 0x15aa2000
	s_addc_u32 s7, s13, 0
	s_add_u32 s8, s12, 0x19ea2000
	s_addc_u32 s9, s13, 0
	s_waitcnt vmcnt(1)
	v_mbcnt_lo_u32_b32 v0, -1, 0
	s_add_u32 s10, s12, 0x15662000
	v_mbcnt_hi_u32_b32 v195, -1, v0
	s_addc_u32 s11, s13, 0
	s_lshl_b32 s23, s22, 9
	s_mov_b32 s23, 0
	s_mov_b64 s[2:3], 0
	v_add_u32_e32 v196, s20, v195
	s_cmp_lt_i32 s78, s23
	v_and_b32_e32 v181, 15, v195
	s_cbranch_scc1 .LBB0_2008
	v_and_b32_e32 v0, 15, v195
	s_branch .LBB0_2009
